# v73 plus memory-attention sample units: second K/V cache staging batch loaded ahead of the first into spare registers (prologue de-serialisation), second loop pass copies instead of loading
# baseline (speedup 1.0000x reference)
; template <bool SAMPLE>
; __device__ __forceinline__ void mem_unit(const Params& p, int l, LAS unsigned char* lds, int unit, int tid, int wave, int lane) {
;     ...
;         for (int hb = 0; hb < 2; ++hb) {
;             float kk[4][8], vv[4][8];
; #pragma unroll
;             for (int it = 0; it < 4; ++it) { const int s = (tid >> 4) + 32 * (4 * hb + it);
;                 const float* kp; const float* vp;
;                 if (!SAMPLE) { kp = (const float*)(p.ws + W_MKV) + ((size_t)l * 1024 + b * 256 + s) * 1024 + h * 128 + sub * 8; vp = kp + 512; }
;                 else { const size_t o = ((((size_t)l * 128 + b) * 256 + s) * 4 + h) * 128 + sub * 8; kp = p.in[I_CMK] + o; vp = p.in[I_CMV] + o; }
;                 if (SAMPLE) { pg8::ld8f_nt(kp, kk[it]); pg8::ld8f_nt(vp, vv[it]); } else { pg8::ld8f(kp, kk[it]); pg8::ld8f(vp, vv[it]); } }
.LBB0_599:
	s_waitcnt vmcnt(1)
	v_add_u32_e32 v66, s8, v81
	v_ashrrev_i32_e32 v67, 31, v66
	v_add_u32_e32 v6, 0x60, v66
	v_lshl_add_u64 v[8:9], v[66:67], 0, s[10:11]
	v_add_u32_e32 v2, 32, v66
	v_add_u32_e32 v4, 64, v66
	v_ashrrev_i32_e32 v7, 31, v6
	v_lshlrev_b64 v[8:9], 11, v[8:9]
	v_ashrrev_i32_e32 v3, 31, v2
	v_ashrrev_i32_e32 v5, 31, v4
	v_lshl_add_u64 v[6:7], v[6:7], 0, s[10:11]
	v_or_b32_e32 v8, v8, v0
	v_lshl_add_u64 v[2:3], v[2:3], 0, s[10:11]
	v_lshl_add_u64 v[4:5], v[4:5], 0, s[10:11]
	v_lshlrev_b64 v[22:23], 11, v[6:7]
	v_lshl_add_u64 v[6:7], s[78:79], 0, v[8:9]
	v_lshl_add_u64 v[14:15], s[80:81], 0, v[8:9]
	v_lshlrev_b64 v[18:19], 11, v[2:3]
	v_lshlrev_b64 v[20:21], 11, v[4:5]
	s_cmp_lg_u32 s8, 0
	s_cbranch_scc1 .Lp6s_it1_0
	s_mov_b32 s100, 0x40000
	s_mov_b32 s101, 0
	v_lshl_add_u64 v[6:7], v[6:7], 0, s[100:101]
	v_lshl_add_u64 v[14:15], v[14:15], 0, s[100:101]
	global_load_dwordx4 v[186:189], v[6:7], off nt
	s_nop 0
	global_load_dwordx4 v[190:193], v[6:7], off offset:16 nt
	s_nop 0
	global_load_dwordx4 v[194:197], v[14:15], off offset:16 nt
	s_nop 0
	global_load_dwordx4 v[198:201], v[14:15], off nt
	s_nop 0
	s_mov_b32 s100, 0xfffc0000
	s_mov_b32 s101, -1
	v_lshl_add_u64 v[6:7], v[6:7], 0, s[100:101]
	v_lshl_add_u64 v[14:15], v[14:15], 0, s[100:101]
	global_load_dwordx4 v[2:5], v[6:7], off nt
	s_nop 0
	global_load_dwordx4 v[6:9], v[6:7], off offset:16 nt
	s_nop 0
	global_load_dwordx4 v[10:13], v[14:15], off offset:16 nt
	s_nop 0
	global_load_dwordx4 v[14:17], v[14:15], off nt
	v_or_b32_e32 v18, v18, v0
	v_or_b32_e32 v20, v20, v0
	v_or_b32_e32 v22, v22, v0
	v_lshl_add_u64 v[24:25], s[78:79], 0, v[18:19]
	v_lshl_add_u64 v[30:31], s[80:81], 0, v[18:19]
	s_waitcnt vmcnt(8)
	v_lshl_add_u64 v[38:39], s[78:79], 0, v[20:21]
	v_lshl_add_u64 v[46:47], s[80:81], 0, v[20:21]
	v_lshl_add_u64 v[54:55], s[78:79], 0, v[22:23]
	v_lshl_add_u64 v[62:63], s[80:81], 0, v[22:23]
	s_mov_b32 s100, 0x40000
	s_mov_b32 s101, 0
	v_lshl_add_u64 v[24:25], v[24:25], 0, s[100:101]
	v_lshl_add_u64 v[30:31], v[30:31], 0, s[100:101]
	v_lshl_add_u64 v[38:39], v[38:39], 0, s[100:101]
	v_lshl_add_u64 v[46:47], v[46:47], 0, s[100:101]
	v_lshl_add_u64 v[54:55], v[54:55], 0, s[100:101]
	v_lshl_add_u64 v[62:63], v[62:63], 0, s[100:101]
	global_load_dwordx4 v[202:205], v[24:25], off nt
	s_nop 0
	global_load_dwordx4 v[206:209], v[24:25], off offset:16 nt
	s_nop 0
	global_load_dwordx4 v[210:213], v[30:31], off nt
	s_nop 0
	global_load_dwordx4 v[218:221], v[30:31], off offset:16 nt
	s_nop 0
	global_load_dwordx4 v[222:225], v[38:39], off nt
	s_nop 0
	global_load_dwordx4 v[226:229], v[38:39], off offset:16 nt
	s_nop 0
	global_load_dwordx4 v[230:233], v[46:47], off nt
	s_nop 0
	global_load_dwordx4 v[234:237], v[46:47], off offset:16 nt
	s_nop 0
	global_load_dwordx4 v[242:245], v[54:55], off nt
	s_nop 0
	global_load_dwordx4 v[246:249], v[54:55], off offset:16 nt
	s_nop 0
	global_load_dwordx4 v[250:253], v[62:63], off nt
	s_nop 0
	global_load_dwordx2 v[214:215], v[62:63], off offset:16 nt
	global_load_dwordx2 v[254:255], v[62:63], off offset:24 nt
	s_nop 0
	s_mov_b32 s100, 0xfffc0000
	s_mov_b32 s101, -1
	v_lshl_add_u64 v[24:25], v[24:25], 0, s[100:101]
	v_lshl_add_u64 v[30:31], v[30:31], 0, s[100:101]
	v_lshl_add_u64 v[38:39], v[38:39], 0, s[100:101]
	v_lshl_add_u64 v[46:47], v[46:47], 0, s[100:101]
	v_lshl_add_u64 v[54:55], v[54:55], 0, s[100:101]
	v_lshl_add_u64 v[62:63], v[62:63], 0, s[100:101]
	global_load_dwordx4 v[18:21], v[24:25], off nt
	s_nop 0
	global_load_dwordx4 v[22:25], v[24:25], off offset:16 nt
	s_nop 0
	global_load_dwordx4 v[26:29], v[30:31], off nt
	s_nop 0
	global_load_dwordx4 v[30:33], v[30:31], off offset:16 nt
	s_nop 0
	global_load_dwordx4 v[34:37], v[38:39], off nt
	s_nop 0
	global_load_dwordx4 v[38:41], v[38:39], off offset:16 nt
	s_nop 0
	global_load_dwordx4 v[42:45], v[46:47], off nt
	s_nop 0
	global_load_dwordx4 v[46:49], v[46:47], off offset:16 nt
	s_nop 0
	global_load_dwordx4 v[50:53], v[54:55], off nt
	s_nop 0
	global_load_dwordx4 v[54:57], v[54:55], off offset:16 nt
	s_nop 0
	global_load_dwordx4 v[58:61], v[62:63], off nt
	s_nop 0
	global_load_dwordx4 v[62:65], v[62:63], off offset:16 nt
	s_branch .Lp6s_join_0
.Lp6s_it1_0:
	s_waitcnt vmcnt(0)
	v_mov_b32_e32 v2, v186
	v_mov_b32_e32 v3, v187
	v_mov_b32_e32 v4, v188
	v_mov_b32_e32 v5, v189
	v_mov_b32_e32 v6, v190
	v_mov_b32_e32 v7, v191
	v_mov_b32_e32 v8, v192
	v_mov_b32_e32 v9, v193
	v_mov_b32_e32 v10, v194
	v_mov_b32_e32 v11, v195
	v_mov_b32_e32 v12, v196
	v_mov_b32_e32 v13, v197
	v_mov_b32_e32 v14, v198
	v_mov_b32_e32 v15, v199
	v_mov_b32_e32 v16, v200
	v_mov_b32_e32 v17, v201
	v_mov_b32_e32 v18, v202
	v_mov_b32_e32 v19, v203
	v_mov_b32_e32 v20, v204
	v_mov_b32_e32 v21, v205
	v_mov_b32_e32 v22, v206
	v_mov_b32_e32 v23, v207
	v_mov_b32_e32 v24, v208
	v_mov_b32_e32 v25, v209
	v_mov_b32_e32 v26, v210
	v_mov_b32_e32 v27, v211
	v_mov_b32_e32 v28, v212
	v_mov_b32_e32 v29, v213
	v_mov_b32_e32 v30, v218
	v_mov_b32_e32 v31, v219
	v_mov_b32_e32 v32, v220
	v_mov_b32_e32 v33, v221
	v_mov_b32_e32 v34, v222
	v_mov_b32_e32 v35, v223
	v_mov_b32_e32 v36, v224
	v_mov_b32_e32 v37, v225
	v_mov_b32_e32 v38, v226
	v_mov_b32_e32 v39, v227
	v_mov_b32_e32 v40, v228
	v_mov_b32_e32 v41, v229
	v_mov_b32_e32 v42, v230
	v_mov_b32_e32 v43, v231
	v_mov_b32_e32 v44, v232
	v_mov_b32_e32 v45, v233
	v_mov_b32_e32 v46, v234
	v_mov_b32_e32 v47, v235
	v_mov_b32_e32 v48, v236
	v_mov_b32_e32 v49, v237
	v_mov_b32_e32 v50, v242
	v_mov_b32_e32 v51, v243
	v_mov_b32_e32 v52, v244
	v_mov_b32_e32 v53, v245
	v_mov_b32_e32 v54, v246
	v_mov_b32_e32 v55, v247
	v_mov_b32_e32 v56, v248
	v_mov_b32_e32 v57, v249
	v_mov_b32_e32 v58, v250
	v_mov_b32_e32 v59, v251
	v_mov_b32_e32 v60, v252
	v_mov_b32_e32 v61, v253
	v_mov_b32_e32 v62, v214
	v_mov_b32_e32 v63, v215
	v_mov_b32_e32 v64, v254
	v_mov_b32_e32 v65, v255
; #define LAS __attribute__((address_space(3)))
; __device__ __forceinline__ void unpack8(const v4u w, float (&o)[8]) { o[0] = bflo(w.x); o[1] = bfhi(w.x); o[2] = bflo(w.y); o[3] = bfhi(w.y); o[4] = bflo(w.z); o[5] = bfhi(w.z); o[6] = bflo(w.w); o[7] = bfhi(w.w); }
; __device__ __forceinline__ bf16x8 pack8(const float (&o)[8]) { v4u w; w.x = pk2(o[0], o[1]); w.y = pk2(o[2], o[3]); w.z = pk2(o[4], o[5]); w.w = pk2(o[6], o[7]); return __builtin_bit_cast(bf16x8, w); }
; template <bool SAMPLE>
; __device__ __forceinline__ void mem_unit(const Params& p, int l, LAS unsigned char* lds, int unit, int tid, int wave, int lane) {
;     ...
;                 *(LAS bf16x8*)(Kl + s * MEM_KS + sub * 8) = pack8(k);
;                 *(LAS bf16x8*)(Vt + s * MEM_VS + sub * 8) = pack8(v);
;             }
;         }
;     }
;     __syncthreads();
;     if (!SAMPLE || wave == 0) {
; #pragma unroll 1
;       for (int qq = 0; qq < (SAMPLE ? 1 : 4); ++qq) {
;         int q16 = lane & 15, kq = lane >> 4; asm volatile("" : "+v"(q16), "+v"(kq));
;         size_t row; bool st;
;         if (!SAMPLE) { row = (size_t)b * 8192 + (qt * 4 + qq) * 128 + 16 * wave + q16; st = true; } else { row = (size_t)MP + 8 * b + (q16 & 7); st = q16 < 8; }
;         bf16x8 qf[4];
;         {
;             float qv[4][8]; float ss = 0.f;
; #pragma unroll
;             for (int dc = 0; dc < 4; ++dc) { unpack8(*(const v4u*)(MQ + row * 512 + h * 128 + 32 * dc + 8 * kq), qv[dc]);
; #pragma unroll
;                 for (int e = 0; e < 8; ++e) ss += qv[dc][e] * qv[dc][e]; }
;             ss += __shfl_xor(ss, 16); ss += __shfl_xor(ss, 32);
;             const float rs = rsqrtf(ss * (1.f / 128.f) + EPS) * 0.08838834764831845f;
.Lp6s_join_0:
	v_cndmask_b32_e64 v1, 0, 1, s[0:1]
	v_cmp_ne_u32_e32 vcc, 1, v1
	v_mul_lo_u32 v1, v66, s30
	v_add_u32_e32 v66, v96, v1
	v_add_u32_e32 v1, v97, v1
	s_movk_i32 s8, 0x80
	s_mov_b64 s[0:1], 0
	s_and_b64 vcc, exec, vcc
	s_waitcnt vmcnt(28)
	v_cvt_pk_bf16_f32 v2, v2, v3
	v_cvt_pk_bf16_f32 v3, v4, v5
	s_waitcnt vmcnt(27)
	v_cvt_pk_bf16_f32 v4, v6, v7
	v_cvt_pk_bf16_f32 v5, v8, v9
	ds_write_b128 v66, v[2:5]
	s_waitcnt vmcnt(25)
	v_cvt_pk_bf16_f32 v2, v14, v15
	v_cvt_pk_bf16_f32 v3, v16, v17
	v_cvt_pk_bf16_f32 v4, v10, v11
	v_cvt_pk_bf16_f32 v5, v12, v13
	ds_write_b128 v1, v[2:5]
	s_waitcnt vmcnt(11)
	v_cvt_pk_bf16_f32 v2, v18, v19
	v_cvt_pk_bf16_f32 v3, v20, v21
	s_waitcnt vmcnt(10)
	v_cvt_pk_bf16_f32 v4, v22, v23
	v_cvt_pk_bf16_f32 v5, v24, v25
	ds_write_b128 v66, v[2:5] offset:8704
	s_waitcnt vmcnt(9)
	v_cvt_pk_bf16_f32 v2, v26, v27
	v_cvt_pk_bf16_f32 v3, v28, v29
	s_waitcnt vmcnt(8)
	v_cvt_pk_bf16_f32 v4, v30, v31
	v_cvt_pk_bf16_f32 v5, v32, v33
	ds_write_b128 v1, v[2:5] offset:8704
	s_waitcnt vmcnt(7)
	v_cvt_pk_bf16_f32 v2, v34, v35
	v_cvt_pk_bf16_f32 v3, v36, v37
	s_waitcnt vmcnt(6)
	v_cvt_pk_bf16_f32 v4, v38, v39
	v_cvt_pk_bf16_f32 v5, v40, v41
	ds_write_b128 v66, v[2:5] offset:17408
	s_waitcnt vmcnt(5)
	v_cvt_pk_bf16_f32 v2, v42, v43
	v_cvt_pk_bf16_f32 v3, v44, v45
	s_waitcnt vmcnt(4)
	v_cvt_pk_bf16_f32 v4, v46, v47
	v_cvt_pk_bf16_f32 v5, v48, v49
	ds_write_b128 v1, v[2:5] offset:17408
	s_waitcnt vmcnt(3)
	v_cvt_pk_bf16_f32 v2, v50, v51
	v_cvt_pk_bf16_f32 v3, v52, v53
	s_waitcnt vmcnt(2)
	v_cvt_pk_bf16_f32 v4, v54, v55
	v_cvt_pk_bf16_f32 v5, v56, v57
	ds_write_b128 v66, v[2:5] offset:26112
	s_waitcnt vmcnt(1)
	v_cvt_pk_bf16_f32 v2, v58, v59
	v_cvt_pk_bf16_f32 v3, v60, v61
	s_waitcnt vmcnt(0)
	v_cvt_pk_bf16_f32 v4, v62, v63
	v_cvt_pk_bf16_f32 v5, v64, v65
	ds_write_b128 v1, v[2:5] offset:26112
	s_cbranch_vccz .LBB0_599
	s_andn2_b64 vcc, exec, s[4:5]
	s_waitcnt lgkmcnt(0)
	s_barrier
	s_cbranch_vccnz .LBB0_618
	s_lshl_b32 s0, s2, 3
	s_add_i32 s1, s0, 0x8000
	s_lshl_b32 s0, s3, 1
	v_mov_b32_e32 v37, v95
	v_mov_b32_e32 v36, v94
	s_add_u32 s2, s64, s0
	s_addc_u32 s3, s65, 0
	v_and_or_b32 v0, v36, 7, s1
	v_lshlrev_b32_e32 v82, 10, v0
	v_lshlrev_b32_e32 v16, 3, v37
	v_lshl_add_u64 v[0:1], s[2:3], 0, v[82:83]
	v_ashrrev_i32_e32 v17, 31, v16
	v_lshl_add_u64 v[12:13], v[16:17], 1, v[0:1]
	global_load_dwordx4 v[0:3], v[12:13], off
	global_load_dwordx4 v[4:7], v[12:13], off offset:64
	global_load_dwordx4 v[8:11], v[12:13], off offset:128
	s_nop 0
	global_load_dwordx4 v[12:15], v[12:13], off offset:192
	v_and_b32_e32 v19, 64, v99
	v_xor_b32_e32 v18, 16, v99
	v_add_u32_e32 v34, 64, v19
	v_cmp_lt_i32_e32 vcc, v18, v34
	v_lshl_add_u64 v[24:25], v[16:17], 2, s[46:47]
	s_waitcnt vmcnt(3)
	v_and_b32_e32 v40, 0xffff0000, v0
	v_cndmask_b32_e32 v18, v99, v18, vcc
	v_lshlrev_b32_e32 v38, 2, v18
	global_load_dwordx4 v[16:19], v[24:25], off offset:16
	global_load_dwordx4 v[20:23], v[24:25], off
	v_lshlrev_b32_e32 v35, 16, v0
	s_waitcnt vmcnt(3)
	v_lshlrev_b32_e32 v55, 16, v8
	v_and_b32_e32 v56, 0xffff0000, v8
	v_mul_f32_e32 v8, v40, v40
	v_lshlrev_b32_e32 v41, 16, v1
	v_fmac_f32_e32 v8, v35, v35
	v_and_b32_e32 v42, 0xffff0000, v1
	v_fmac_f32_e32 v8, v41, v41
	v_lshlrev_b32_e32 v43, 16, v2
	v_fmac_f32_e32 v8, v42, v42
	v_and_b32_e32 v44, 0xffff0000, v2
	v_fmac_f32_e32 v8, v43, v43
	v_lshlrev_b32_e32 v45, 16, v3
	v_fmac_f32_e32 v8, v44, v44
	v_and_b32_e32 v46, 0xffff0000, v3
	v_fmac_f32_e32 v8, v45, v45
	v_lshlrev_b32_e32 v47, 16, v4
	v_fmac_f32_e32 v8, v46, v46
	v_and_b32_e32 v48, 0xffff0000, v4
	v_fmac_f32_e32 v8, v47, v47
	v_lshlrev_b32_e32 v49, 16, v5
	v_fmac_f32_e32 v8, v48, v48
	v_and_b32_e32 v50, 0xffff0000, v5
	v_fmac_f32_e32 v8, v49, v49
	v_lshlrev_b32_e32 v51, 16, v6
	v_fmac_f32_e32 v8, v50, v50
	v_and_b32_e32 v52, 0xffff0000, v6
	v_fmac_f32_e32 v8, v51, v51
	v_lshlrev_b32_e32 v53, 16, v7
	v_fmac_f32_e32 v8, v52, v52
	v_and_b32_e32 v54, 0xffff0000, v7
	v_fmac_f32_e32 v8, v53, v53
	v_fmac_f32_e32 v8, v54, v54
	v_fmac_f32_e32 v8, v55, v55
	v_lshlrev_b32_e32 v57, 16, v9
	v_fmac_f32_e32 v8, v56, v56
	v_and_b32_e32 v58, 0xffff0000, v9
	v_fmac_f32_e32 v8, v57, v57
	v_lshlrev_b32_e32 v59, 16, v10
	v_fmac_f32_e32 v8, v58, v58
	v_and_b32_e32 v60, 0xffff0000, v10
	v_fmac_f32_e32 v8, v59, v59
	v_lshlrev_b32_e32 v61, 16, v11
	v_fmac_f32_e32 v8, v60, v60
	v_and_b32_e32 v62, 0xffff0000, v11
	s_waitcnt vmcnt(2)
	v_and_b32_e32 v26, 0xffff0000, v12
	v_lshlrev_b32_e32 v27, 16, v12
	v_fmac_f32_e32 v8, v61, v61
	v_pk_mul_f32 v[0:1], v[26:27], v[26:27]
	v_fmac_f32_e32 v8, v62, v62
	v_and_b32_e32 v28, 0xffff0000, v13
	v_lshlrev_b32_e32 v29, 16, v13
	v_add_f32_e32 v1, v1, v8
	v_pk_mul_f32 v[2:3], v[28:29], v[28:29]
	v_add_f32_e32 v0, v0, v1
	v_and_b32_e32 v30, 0xffff0000, v14
	v_lshlrev_b32_e32 v31, 16, v14
	v_add_f32_e32 v0, v3, v0
	v_pk_mul_f32 v[4:5], v[30:31], v[30:31]
	v_add_f32_e32 v0, v2, v0
	v_and_b32_e32 v32, 0xffff0000, v15
	v_lshlrev_b32_e32 v33, 16, v15
	v_add_f32_e32 v0, v5, v0
	v_pk_mul_f32 v[6:7], v[32:33], v[32:33]
	v_add_f32_e32 v0, v4, v0
	v_add_f32_e32 v0, v7, v0
	v_add_f32_e32 v0, v6, v0
	ds_bpermute_b32 v1, v38, v0
	v_xor_b32_e32 v2, 32, v99
	v_cmp_lt_i32_e32 vcc, v2, v34
	s_waitcnt lgkmcnt(0)
	v_add_f32_e32 v0, v0, v1
	v_cndmask_b32_e32 v2, v99, v2, vcc
	v_lshlrev_b32_e32 v39, 2, v2
	ds_bpermute_b32 v1, v39, v0
	s_waitcnt lgkmcnt(0)
	v_add_f32_e32 v0, v0, v1
	v_fmamk_f32 v0, v0, 0x3c000000, v98
	v_mul_f32_e32 v1, 0x4b800000, v0
	v_cmp_gt_f32_e32 vcc, s31, v0
	s_nop 1
	v_cndmask_b32_e32 v0, v0, v1, vcc
	v_rsq_f32_e32 v0, v0
	s_nop 0
	v_mul_f32_e32 v1, 0x45800000, v0
	v_cndmask_b32_e32 v0, v0, v1, vcc
	v_mul_f32_e32 v34, 0x3db504f3, v0
	s_waitcnt vmcnt(0)
; #define LAS __attribute__((address_space(3)))
; __device__ __forceinline__ bf16x8 pack8(const float (&o)[8]) { v4u w; w.x = pk2(o[0], o[1]); w.y = pk2(o[2], o[3]); w.z = pk2(o[4], o[5]); w.w = pk2(o[6], o[7]); return __builtin_bit_cast(bf16x8, w); }
; template <bool SAMPLE>
; __device__ __forceinline__ void mem_unit(const Params& p, int l, LAS unsigned char* lds, int unit, int tid, int wave, int lane) {
;     ...
; #pragma unroll
;             for (int dc = 0; dc < 4; ++dc) { float qg[8]; pg8::ld8f(p.in[I_MQG] + l * 128 + 32 * dc + 8 * kq, qg);
; #pragma unroll
;                 for (int e = 0; e < 8; ++e) qv[dc][e] *= rs * qg[e];
;                 qf[dc] = pack8(qv[dc]); }
;         }
;         f32x4 S[8][2]; float mx = -INFINITY;
; #pragma unroll
;         for (int cc = 0; cc < 8; ++cc)
; #pragma unroll
;             for (int tt = 0; tt < 2; ++tt) { const int kb = 32 * cc + 16 * tt; f32x4 a = (f32x4){0.f, 0.f, 0.f, 0.f};
; #pragma unroll
;                 for (int dc = 0; dc < 4; ++dc) { const bf16x8 kf = *(const LAS bf16x8*)(Kl + (kb + q16) * MEM_KS + 32 * dc + 8 * kq);
;                     a = __builtin_amdgcn_mfma_f32_16x16x32_bf16(kf, qf[dc], a, 0, 0, 0); }
	v_mul_f32_e32 v0, v20, v34
	v_mul_f32_e32 v1, v21, v34
	v_mul_f32_e32 v2, v22, v34
	v_mul_f32_e32 v3, v23, v34
	v_mul_f32_e32 v4, v16, v34
	v_mul_f32_e32 v5, v17, v34
	v_mul_f32_e32 v6, v18, v34
	v_mul_f32_e32 v7, v19, v34
	v_mul_f32_e32 v0, v0, v35
	v_mul_f32_e32 v1, v1, v40
	v_mul_f32_e32 v2, v2, v41
	v_mul_f32_e32 v3, v3, v42
	v_mul_f32_e32 v4, v4, v43
	v_mul_f32_e32 v5, v5, v44
	v_mul_f32_e32 v6, v6, v45
	v_mul_f32_e32 v7, v7, v46
	v_cvt_pk_bf16_f32 v0, v0, v1
	v_cvt_pk_bf16_f32 v1, v2, v3
	v_cvt_pk_bf16_f32 v2, v4, v5
	v_cvt_pk_bf16_f32 v3, v6, v7
	global_load_dwordx4 v[4:7], v[24:25], off offset:128
	global_load_dwordx4 v[8:11], v[24:25], off offset:144
	v_lshlrev_b32_e32 v20, 4, v37
	v_mul_lo_u32 v21, v36, s30
	v_add3_u32 v92, 0, v20, v21
	s_waitcnt vmcnt(1)
	v_mul_f32_e32 v4, v4, v34
	v_mul_f32_e32 v5, v5, v34
	v_mul_f32_e32 v6, v6, v34
	v_mul_f32_e32 v7, v7, v34
	s_waitcnt vmcnt(0)
	v_mul_f32_e32 v8, v8, v34
	v_mul_f32_e32 v9, v9, v34
	v_mul_f32_e32 v10, v10, v34
	v_mul_f32_e32 v11, v11, v34
	v_mul_f32_e32 v4, v4, v47
	v_mul_f32_e32 v5, v5, v48
	v_mul_f32_e32 v6, v6, v49
	v_mul_f32_e32 v7, v7, v50
	v_mul_f32_e32 v12, v8, v51
	v_mul_f32_e32 v13, v9, v52
	v_mul_f32_e32 v14, v10, v53
	v_mul_f32_e32 v11, v11, v54
	v_cvt_pk_bf16_f32 v8, v4, v5
	v_cvt_pk_bf16_f32 v9, v6, v7
	v_cvt_pk_bf16_f32 v10, v12, v13
	v_cvt_pk_bf16_f32 v11, v14, v11
	global_load_dwordx4 v[4:7], v[24:25], off offset:256
	global_load_dwordx4 v[12:15], v[24:25], off offset:272
	s_waitcnt vmcnt(1)
	v_mul_f32_e32 v4, v4, v34
	v_mul_f32_e32 v5, v5, v34
	v_mul_f32_e32 v6, v6, v34
	v_mul_f32_e32 v7, v7, v34
	s_waitcnt vmcnt(0)
	v_mul_f32_e32 v12, v12, v34
	v_mul_f32_e32 v13, v13, v34
	v_mul_f32_e32 v14, v14, v34
	v_mul_f32_e32 v15, v15, v34
	v_mul_f32_e32 v4, v4, v55
	v_mul_f32_e32 v5, v5, v56
	v_mul_f32_e32 v6, v6, v57
	v_mul_f32_e32 v7, v7, v58
	v_mul_f32_e32 v12, v12, v59
	v_mul_f32_e32 v13, v13, v60
	v_mul_f32_e32 v14, v14, v61
	v_mul_f32_e32 v15, v15, v62
	v_cvt_pk_bf16_f32 v4, v4, v5
	v_cvt_pk_bf16_f32 v5, v6, v7
	v_cvt_pk_bf16_f32 v6, v12, v13
	v_cvt_pk_bf16_f32 v7, v14, v15
	global_load_dwordx4 v[12:15], v[24:25], off offset:384
	global_load_dwordx4 v[16:19], v[24:25], off offset:400
	s_waitcnt vmcnt(1)
	v_mul_f32_e32 v12, v12, v34
	v_mul_f32_e32 v13, v13, v34
	v_mul_f32_e32 v14, v14, v34
	v_mul_f32_e32 v15, v15, v34
	s_waitcnt vmcnt(0)
	v_mul_f32_e32 v16, v16, v34
	v_mul_f32_e32 v17, v17, v34
	v_mul_f32_e32 v18, v18, v34
	v_mul_f32_e32 v19, v19, v34
	v_mul_f32_e32 v12, v12, v27
	v_mul_f32_e32 v13, v13, v26
	v_mul_f32_e32 v14, v14, v29
	v_mul_f32_e32 v15, v15, v28
	v_mul_f32_e32 v16, v16, v31
	v_mul_f32_e32 v17, v17, v30
	v_mul_f32_e32 v18, v18, v33
	v_mul_f32_e32 v19, v19, v32
	v_cvt_pk_bf16_f32 v32, v12, v13
	v_cvt_pk_bf16_f32 v33, v14, v15
	v_cvt_pk_bf16_f32 v34, v16, v17
	v_cvt_pk_bf16_f32 v35, v18, v19
	ds_read_b128 v[186:189], v92
	ds_read_b128 v[190:193], v92 offset:4352
	ds_read_b128 v[194:197], v92 offset:8704
	ds_read_b128 v[198:201], v92 offset:13056
	ds_read_b128 v[202:205], v92 offset:17408
	s_nop 0
	ds_read_b128 v[16:19], v92 offset:64
	s_nop 0
	ds_read_b128 v[24:27], v92 offset:4416
	s_nop 0
	ds_read_b128 v[40:43], v92 offset:8768
	s_nop 0
	ds_read_b128 v[48:51], v92 offset:13120
	s_nop 0
	ds_read_b128 v[56:59], v92 offset:17472
	ds_read_b128 v[60:63], v92 offset:21760
	ds_read_b128 v[64:67], v92 offset:21824
	ds_read_b128 v[68:71], v92 offset:26112
	ds_read_b128 v[72:75], v92 offset:26176
	ds_read_b128 v[76:79], v92 offset:30464
	ds_read_b128 v[88:91], v92 offset:30528
	ds_read_b128 v[100:103], v92 offset:34816
	ds_read_b128 v[104:107], v92 offset:34880
	ds_read_b128 v[108:111], v92 offset:39168
	ds_read_b128 v[112:115], v92 offset:39232
	ds_read_b128 v[116:119], v92 offset:43520
	ds_read_b128 v[120:123], v92 offset:43584
	ds_read_b128 v[124:127], v92 offset:47872
	ds_read_b128 v[128:131], v92 offset:47936
	ds_read_b128 v[132:135], v92 offset:52224
	ds_read_b128 v[136:139], v92 offset:52288
	ds_read_b128 v[140:143], v92 offset:56576
	ds_read_b128 v[144:147], v92 offset:56640
	ds_read_b128 v[148:151], v92 offset:60928
	ds_read_b128 v[152:155], v92 offset:60992
	ds_read_b128 v[156:159], v92 offset:65280
	ds_read_b128 v[160:163], v92 offset:65344
	s_waitcnt lgkmcnt(14)
	v_mfma_f32_16x16x32_bf16 v[12:15], v[186:189], v[0:3], 0
	v_mfma_f32_16x16x32_bf16 v[20:23], v[190:193], v[0:3], 0
	v_mfma_f32_16x16x32_bf16 v[28:31], v[194:197], v[0:3], 0
	v_mfma_f32_16x16x32_bf16 v[44:47], v[198:201], v[0:3], 0
	v_mfma_f32_16x16x32_bf16 v[52:55], v[202:205], v[0:3], 0
	v_mfma_f32_16x16x32_bf16 v[60:63], v[60:63], v[0:3], 0
	v_mfma_f32_16x16x32_bf16 v[68:71], v[68:71], v[0:3], 0
	v_mfma_f32_16x16x32_bf16 v[76:79], v[76:79], v[0:3], 0
	v_mfma_f32_16x16x32_bf16 v[100:103], v[100:103], v[0:3], 0
	s_waitcnt lgkmcnt(13)
	v_mfma_f32_16x16x32_bf16 v[108:111], v[108:111], v[0:3], 0
	s_waitcnt lgkmcnt(11)
	v_mfma_f32_16x16x32_bf16 v[116:119], v[116:119], v[0:3], 0
	s_waitcnt lgkmcnt(9)
	v_mfma_f32_16x16x32_bf16 v[124:127], v[124:127], v[0:3], 0
	s_waitcnt lgkmcnt(7)
	v_mfma_f32_16x16x32_bf16 v[132:135], v[132:135], v[0:3], 0
	s_waitcnt lgkmcnt(5)
	v_mfma_f32_16x16x32_bf16 v[140:143], v[140:143], v[0:3], 0
	s_waitcnt lgkmcnt(3)
	v_mfma_f32_16x16x32_bf16 v[148:151], v[148:151], v[0:3], 0
	s_waitcnt lgkmcnt(1)
; #define LAS __attribute__((address_space(3)))
; template <bool SAMPLE>
; __device__ __forceinline__ void mem_unit(const Params& p, int l, LAS unsigned char* lds, int unit, int tid, int wave, int lane) {
;     ...
;         for (int cc = 0; cc < 8; ++cc)
; #pragma unroll
;             for (int tt = 0; tt < 2; ++tt) { const int kb = 32 * cc + 16 * tt; f32x4 a = (f32x4){0.f, 0.f, 0.f, 0.f};
; #pragma unroll
;                 for (int dc = 0; dc < 4; ++dc) { const bf16x8 kf = *(const LAS bf16x8*)(Kl + (kb + q16) * MEM_KS + 32 * dc + 8 * kq);
;                     a = __builtin_amdgcn_mfma_f32_16x16x32_bf16(kf, qf[dc], a, 0, 0, 0); }
; #pragma unroll
;                 for (int e = 0; e < 4; ++e) mx = fmaxf(mx, a[e]);
;                 S[cc][tt] = a; }
	v_mfma_f32_16x16x32_bf16 v[0:3], v[156:159], v[0:3], 0
	v_mfma_f32_16x16x32_bf16 v[12:15], v[16:19], v[8:11], v[12:15]
	v_mfma_f32_16x16x32_bf16 v[16:19], v[24:27], v[8:11], v[20:23]
	v_mfma_f32_16x16x32_bf16 v[20:23], v[40:43], v[8:11], v[28:31]
	v_mfma_f32_16x16x32_bf16 v[24:27], v[48:51], v[8:11], v[44:47]
	v_mfma_f32_16x16x32_bf16 v[28:31], v[56:59], v[8:11], v[52:55]
	v_mfma_f32_16x16x32_bf16 v[40:43], v[64:67], v[8:11], v[60:63]
	v_mfma_f32_16x16x32_bf16 v[44:47], v[72:75], v[8:11], v[68:71]
	v_mfma_f32_16x16x32_bf16 v[48:51], v[88:91], v[8:11], v[76:79]
	v_mfma_f32_16x16x32_bf16 v[52:55], v[104:107], v[8:11], v[100:103]
	ds_read_b128 v[190:193], v92 offset:128
	ds_read_b128 v[194:197], v92 offset:4480
	ds_read_b128 v[198:201], v92 offset:8832
	ds_read_b128 v[202:205], v92 offset:13184
	v_mfma_f32_16x16x32_bf16 v[56:59], v[112:115], v[8:11], v[108:111]
	v_mfma_f32_16x16x32_bf16 v[60:63], v[120:123], v[8:11], v[116:119]
	v_mfma_f32_16x16x32_bf16 v[64:67], v[128:131], v[8:11], v[124:127]
	v_mfma_f32_16x16x32_bf16 v[68:71], v[136:139], v[8:11], v[132:135]
	v_mfma_f32_16x16x32_bf16 v[72:75], v[144:147], v[8:11], v[140:143]
	ds_read_b128 v[206:209], v92 offset:17536
	ds_read_b128 v[210:213], v92 offset:21888
	ds_read_b128 v[218:221], v92 offset:26240
	ds_read_b128 v[222:225], v92 offset:30592
	ds_read_b128 v[226:229], v92 offset:34944
	v_mfma_f32_16x16x32_bf16 v[76:79], v[152:155], v[8:11], v[148:151]
	s_waitcnt lgkmcnt(9)
	v_mfma_f32_16x16x32_bf16 v[0:3], v[160:163], v[8:11], v[0:3]
	s_nop 0
	ds_read_b128 v[88:91], v92 offset:192
	s_waitcnt lgkmcnt(9)
	v_mfma_f32_16x16x32_bf16 v[8:11], v[190:193], v[4:7], v[12:15]
	s_nop 2
	s_nop 0
	ds_read_b128 v[100:103], v92 offset:4544
	s_waitcnt lgkmcnt(9)
	v_mfma_f32_16x16x32_bf16 v[12:15], v[194:197], v[4:7], v[16:19]
	s_nop 2
	s_nop 0
	ds_read_b128 v[104:107], v92 offset:8896
	s_waitcnt lgkmcnt(9)
	v_mfma_f32_16x16x32_bf16 v[16:19], v[198:201], v[4:7], v[20:23]
	s_nop 2
	s_nop 0
	ds_read_b128 v[108:111], v92 offset:13248
	s_waitcnt lgkmcnt(9)
	v_mfma_f32_16x16x32_bf16 v[20:23], v[202:205], v[4:7], v[24:27]
	s_nop 2
	s_nop 0
	ds_read_b128 v[112:115], v92 offset:17600
	s_waitcnt lgkmcnt(9)
	ds_read_b128 v[186:189], v92 offset:39296
	ds_read_b128 v[190:193], v92 offset:43648
	ds_read_b128 v[194:197], v92 offset:48000
	ds_read_b128 v[198:201], v92 offset:52352
	ds_read_b128 v[202:205], v92 offset:56704
	v_mfma_f32_16x16x32_bf16 v[24:27], v[206:209], v[4:7], v[28:31]
	s_nop 2
	s_nop 0
	ds_read_b128 v[116:119], v92 offset:21952
	s_waitcnt lgkmcnt(14)
	v_mfma_f32_16x16x32_bf16 v[28:31], v[210:213], v[4:7], v[40:43]
	s_nop 2
	s_nop 0
	ds_read_b128 v[120:123], v92 offset:26304
	s_waitcnt lgkmcnt(14)
	v_mfma_f32_16x16x32_bf16 v[40:43], v[218:221], v[4:7], v[44:47]
	s_nop 2
	s_nop 0
	ds_read_b128 v[124:127], v92 offset:30656
	s_waitcnt lgkmcnt(14)
	v_mfma_f32_16x16x32_bf16 v[44:47], v[222:225], v[4:7], v[48:51]
	s_nop 2
	s_nop 0
	ds_read_b128 v[128:131], v92 offset:35008
	s_waitcnt lgkmcnt(14)
	v_mfma_f32_16x16x32_bf16 v[48:51], v[226:229], v[4:7], v[52:55]
	s_nop 2
	s_nop 0
	ds_read_b128 v[132:135], v92 offset:39360
	s_waitcnt lgkmcnt(9)
	ds_read_b128 v[206:209], v92 offset:61056
	ds_read_b128 v[210:213], v92 offset:65408
	v_mfma_f32_16x16x32_bf16 v[52:55], v[186:189], v[4:7], v[56:59]
	s_nop 2
	s_nop 0
	ds_read_b128 v[136:139], v92 offset:43712
	s_waitcnt lgkmcnt(11)
	v_mfma_f32_16x16x32_bf16 v[56:59], v[190:193], v[4:7], v[60:63]
	s_nop 2
	s_nop 0
	ds_read_b128 v[140:143], v92 offset:48064
	s_waitcnt lgkmcnt(11)
	v_mfma_f32_16x16x32_bf16 v[60:63], v[194:197], v[4:7], v[64:67]
	s_nop 2
	s_nop 0
	ds_read_b128 v[144:147], v92 offset:52416
	s_waitcnt lgkmcnt(11)
	v_mfma_f32_16x16x32_bf16 v[64:67], v[198:201], v[4:7], v[68:71]
	s_nop 2
	s_nop 0
	ds_read_b128 v[148:151], v92 offset:56768
	s_waitcnt lgkmcnt(11)
	v_mfma_f32_16x16x32_bf16 v[68:71], v[202:205], v[4:7], v[72:75]
	s_nop 2
	s_nop 0
	ds_read_b128 v[152:155], v92 offset:61120
	s_waitcnt lgkmcnt(6)
	v_mfma_f32_16x16x32_bf16 v[72:75], v[206:209], v[4:7], v[76:79]
	s_nop 2
	s_nop 0
	ds_read_b128 v[156:159], v92 offset:65472
	s_waitcnt lgkmcnt(6)
	v_mfma_f32_16x16x32_bf16 v[0:3], v[210:213], v[4:7], v[0:3]
	v_mfma_f32_16x16x32_bf16 v[76:79], v[88:91], v[32:35], v[8:11]
	v_mfma_f32_16x16x32_bf16 v[88:91], v[100:103], v[32:35], v[12:15]
	v_mfma_f32_16x16x32_bf16 v[100:103], v[104:107], v[32:35], v[16:19]
	v_mfma_f32_16x16x32_bf16 v[104:107], v[108:111], v[32:35], v[20:23]
	v_mfma_f32_16x16x32_bf16 v[108:111], v[112:115], v[32:35], v[24:27]
	v_mfma_f32_16x16x32_bf16 v[112:115], v[116:119], v[32:35], v[28:31]
	v_mfma_f32_16x16x32_bf16 v[40:43], v[120:123], v[32:35], v[40:43]
	v_mfma_f32_16x16x32_bf16 v[44:47], v[124:127], v[32:35], v[44:47]
	v_mfma_f32_16x16x32_bf16 v[28:31], v[128:131], v[32:35], v[48:51]
	v_mfma_f32_16x16x32_bf16 v[24:27], v[132:135], v[32:35], v[52:55]
	v_mfma_f32_16x16x32_bf16 v[20:23], v[136:139], v[32:35], v[56:59]
	v_mfma_f32_16x16x32_bf16 v[16:19], v[140:143], v[32:35], v[60:63]
	v_mfma_f32_16x16x32_bf16 v[12:15], v[144:147], v[32:35], v[64:67]
	v_mfma_f32_16x16x32_bf16 v[8:11], v[148:151], v[32:35], v[68:71]
	v_mfma_f32_16x16x32_bf16 v[4:7], v[152:155], v[32:35], v[72:75]
	s_waitcnt lgkmcnt(0)
; template <bool SAMPLE>
; __device__ __forceinline__ void mem_unit(const Params& p, int l, LAS unsigned char* lds, int unit, int tid, int wave, int lane) {
;     ...
;                 for (int e = 0; e < 4; ++e) mx = fmaxf(mx, a[e]);
;                 S[cc][tt] = a; }
;         mx = fmaxf(mx, __shfl_xor(mx, 16)); mx = fmaxf(mx, __shfl_xor(mx, 32));
;         float den = 0.f;
; #pragma unroll
;         for (int cc = 0; cc < 8; ++cc)
; #pragma unroll
;             for (int tt = 0; tt < 2; ++tt)
; #pragma unroll
;                 for (int e = 0; e < 4; ++e) { const float pe = __expf(S[cc][tt][e] - mx); S[cc][tt][e] = pe; den += pe; }
	v_mfma_f32_16x16x32_bf16 v[0:3], v[156:159], v[32:35], v[0:3]
	v_max3_f32 v32, v76, s33, v77
	v_max3_f32 v32, v32, v78, v79
	v_max3_f32 v32, v32, v88, v89
	v_max3_f32 v32, v32, v90, v91
	v_max3_f32 v32, v32, v100, v101
	v_max3_f32 v32, v32, v102, v103
	v_max3_f32 v32, v32, v104, v105
	v_max3_f32 v32, v32, v106, v107
	v_max3_f32 v32, v32, v108, v109
	v_max3_f32 v32, v32, v110, v111
	v_max3_f32 v32, v32, v112, v113
	v_max3_f32 v32, v32, v114, v115
	v_max3_f32 v32, v32, v40, v41
	v_max3_f32 v32, v32, v42, v43
	v_max3_f32 v32, v32, v44, v45
	v_max3_f32 v32, v32, v46, v47
	v_max3_f32 v32, v32, v28, v29
	v_max3_f32 v32, v32, v30, v31
	v_max3_f32 v32, v32, v24, v25
	v_max3_f32 v32, v32, v26, v27
	v_max3_f32 v32, v32, v20, v21
	v_max3_f32 v32, v32, v22, v23
	v_max3_f32 v32, v32, v16, v17
	v_max3_f32 v32, v32, v18, v19
	v_max3_f32 v32, v32, v12, v13
	v_max3_f32 v32, v32, v14, v15
	v_max3_f32 v32, v32, v8, v9
	v_max3_f32 v32, v32, v10, v11
	v_max3_f32 v32, v32, v4, v5
	v_max3_f32 v32, v32, v6, v7
	v_max3_f32 v32, v32, v0, v1
	v_max3_f32 v32, v32, v2, v3
	ds_bpermute_b32 v33, v38, v32
	s_waitcnt lgkmcnt(0)
	v_max_f32_e32 v33, v33, v33
	v_max_f32_e32 v32, v32, v33
	ds_bpermute_b32 v33, v39, v32
	s_waitcnt lgkmcnt(0)
	v_max_f32_e32 v33, v33, v33
	v_max_f32_e32 v32, v32, v33
	v_sub_f32_e32 v33, v76, v32
	v_sub_f32_e32 v34, v77, v32
	v_mul_f32_e32 v33, 0x3fb8aa3b, v33
	v_sub_f32_e32 v35, v78, v32
	v_mul_f32_e32 v34, 0x3fb8aa3b, v34
	v_exp_f32_e32 v33, v33
	v_sub_f32_e32 v48, v79, v32
	v_mul_f32_e32 v35, 0x3fb8aa3b, v35
	v_exp_f32_e32 v34, v34
	v_sub_f32_e32 v49, v88, v32
	v_mul_f32_e32 v48, 0x3fb8aa3b, v48
	v_exp_f32_e32 v35, v35
	v_sub_f32_e32 v50, v89, v32
	v_mul_f32_e32 v49, 0x3fb8aa3b, v49
	v_exp_f32_e32 v48, v48
	v_sub_f32_e32 v51, v90, v32
	v_mul_f32_e32 v50, 0x3fb8aa3b, v50
	v_exp_f32_e32 v49, v49
	v_add_f32_e32 v69, 0, v33
	v_sub_f32_e32 v52, v91, v32
	v_mul_f32_e32 v51, 0x3fb8aa3b, v51
	v_exp_f32_e32 v50, v50
	v_add_f32_e32 v69, v34, v69
	v_sub_f32_e32 v53, v100, v32
	v_mul_f32_e32 v52, 0x3fb8aa3b, v52
	v_exp_f32_e32 v51, v51
	v_add_f32_e32 v69, v35, v69
	v_sub_f32_e32 v54, v101, v32
	v_mul_f32_e32 v53, 0x3fb8aa3b, v53
	v_exp_f32_e32 v52, v52
	v_add_f32_e32 v69, v48, v69
	v_sub_f32_e32 v55, v102, v32
	v_mul_f32_e32 v54, 0x3fb8aa3b, v54
	v_exp_f32_e32 v53, v53
	v_add_f32_e32 v69, v49, v69
	v_sub_f32_e32 v56, v103, v32
	v_mul_f32_e32 v55, 0x3fb8aa3b, v55
	v_exp_f32_e32 v54, v54
	v_add_f32_e32 v69, v50, v69
	v_sub_f32_e32 v57, v104, v32
	v_mul_f32_e32 v56, 0x3fb8aa3b, v56
	v_exp_f32_e32 v55, v55
	v_add_f32_e32 v69, v51, v69
	v_sub_f32_e32 v58, v105, v32
	v_mul_f32_e32 v57, 0x3fb8aa3b, v57
	v_exp_f32_e32 v56, v56
	v_add_f32_e32 v69, v52, v69
	v_sub_f32_e32 v59, v106, v32
	v_mul_f32_e32 v58, 0x3fb8aa3b, v58
	v_exp_f32_e32 v57, v57
	v_add_f32_e32 v69, v53, v69
	v_sub_f32_e32 v60, v107, v32
	v_mul_f32_e32 v59, 0x3fb8aa3b, v59
	v_exp_f32_e32 v58, v58
	v_add_f32_e32 v69, v54, v69
	v_sub_f32_e32 v61, v108, v32
	v_mul_f32_e32 v60, 0x3fb8aa3b, v60
	v_exp_f32_e32 v59, v59
	v_add_f32_e32 v69, v55, v69
	v_sub_f32_e32 v62, v109, v32
	v_mul_f32_e32 v61, 0x3fb8aa3b, v61
	v_exp_f32_e32 v60, v60
	v_add_f32_e32 v69, v56, v69
	v_sub_f32_e32 v63, v110, v32
	v_mul_f32_e32 v62, 0x3fb8aa3b, v62
	v_exp_f32_e32 v61, v61
	v_add_f32_e32 v69, v57, v69
	v_sub_f32_e32 v64, v111, v32
	v_mul_f32_e32 v63, 0x3fb8aa3b, v63
	v_exp_f32_e32 v62, v62
	v_add_f32_e32 v69, v58, v69
	v_sub_f32_e32 v65, v112, v32
	v_mul_f32_e32 v64, 0x3fb8aa3b, v64
	v_exp_f32_e32 v63, v63
	v_add_f32_e32 v69, v59, v69
	v_sub_f32_e32 v66, v113, v32
	v_mul_f32_e32 v65, 0x3fb8aa3b, v65
	v_exp_f32_e32 v64, v64
	v_add_f32_e32 v69, v60, v69
	v_sub_f32_e32 v67, v114, v32
	v_mul_f32_e32 v66, 0x3fb8aa3b, v66
	v_exp_f32_e32 v65, v65
	v_add_f32_e32 v69, v61, v69
	v_sub_f32_e32 v68, v115, v32
	v_mul_f32_e32 v67, 0x3fb8aa3b, v67
	v_exp_f32_e32 v66, v66
	v_add_f32_e32 v69, v62, v69
	v_sub_f32_e32 v40, v40, v32
	v_mul_f32_e32 v68, 0x3fb8aa3b, v68
	v_exp_f32_e32 v67, v67
	v_add_f32_e32 v69, v63, v69
	v_sub_f32_e32 v41, v41, v32
	v_mul_f32_e32 v40, 0x3fb8aa3b, v40
	v_exp_f32_e32 v68, v68
	v_add_f32_e32 v69, v64, v69
	v_sub_f32_e32 v42, v42, v32
	v_mul_f32_e32 v41, 0x3fb8aa3b, v41
	v_exp_f32_e32 v40, v40
	v_add_f32_e32 v69, v65, v69
	v_sub_f32_e32 v43, v43, v32
	v_mul_f32_e32 v42, 0x3fb8aa3b, v42
	v_exp_f32_e32 v41, v41
	v_add_f32_e32 v69, v66, v69
	v_sub_f32_e32 v44, v44, v32
	v_mul_f32_e32 v43, 0x3fb8aa3b, v43
	v_exp_f32_e32 v42, v42
	v_add_f32_e32 v69, v67, v69
	v_sub_f32_e32 v45, v45, v32
	v_mul_f32_e32 v44, 0x3fb8aa3b, v44
	v_exp_f32_e32 v43, v43
	v_add_f32_e32 v69, v68, v69
	v_sub_f32_e32 v46, v46, v32
	v_mul_f32_e32 v45, 0x3fb8aa3b, v45
	v_exp_f32_e32 v44, v44
	v_add_f32_e32 v69, v40, v69
	v_sub_f32_e32 v47, v47, v32
	v_mul_f32_e32 v46, 0x3fb8aa3b, v46
	v_exp_f32_e32 v45, v45
	v_add_f32_e32 v69, v41, v69
	v_sub_f32_e32 v28, v28, v32
	v_mul_f32_e32 v47, 0x3fb8aa3b, v47
	v_exp_f32_e32 v46, v46
	v_add_f32_e32 v69, v42, v69
	v_sub_f32_e32 v29, v29, v32
	v_mul_f32_e32 v28, 0x3fb8aa3b, v28
	v_exp_f32_e32 v47, v47
	v_add_f32_e32 v69, v43, v69
	v_exp_f32_e32 v28, v28
	v_add_f32_e32 v69, v44, v69
	v_mul_f32_e32 v29, 0x3fb8aa3b, v29
	v_sub_f32_e32 v30, v30, v32
	v_sub_f32_e32 v24, v24, v32
	v_add_f32_e32 v69, v45, v69
	v_exp_f32_e32 v29, v29
	v_mul_f32_e32 v30, 0x3fb8aa3b, v30
	v_sub_f32_e32 v31, v31, v32
	v_mul_f32_e32 v24, 0x3fb8aa3b, v24
	v_add_f32_e32 v69, v46, v69
	v_exp_f32_e32 v30, v30
	v_mul_f32_e32 v31, 0x3fb8aa3b, v31
	v_exp_f32_e32 v70, v24
	v_sub_f32_e32 v24, v25, v32
	v_add_f32_e32 v69, v47, v69
	v_exp_f32_e32 v31, v31
	v_mul_f32_e32 v24, 0x3fb8aa3b, v24
	v_add_f32_e32 v69, v28, v69
	v_exp_f32_e32 v71, v24
; #define LAS __attribute__((address_space(3)))
; __device__ __forceinline__ unsigned pk2(float lo, float hi) { return pg8::cvt_pk_bf16(lo, hi); }
; __device__ __forceinline__ bf16x8 pack8(const float (&o)[8]) { v4u w; w.x = pk2(o[0], o[1]); w.y = pk2(o[2], o[3]); w.z = pk2(o[4], o[5]); w.w = pk2(o[6], o[7]); return __builtin_bit_cast(bf16x8, w); }
; __device__ __forceinline__ v2u vtr(const LAS bf16* p) { return __builtin_bit_cast(v2u, __builtin_amdgcn_ds_read_tr16_b64_v4i16((LAS v4i16_t*)p)); }
; template <bool SAMPLE>
; __device__ __forceinline__ void mem_unit(const Params& p, int l, LAS unsigned char* lds, int unit, int tid, int wave, int lane) {
;     ...
;                 for (int e = 0; e < 4; ++e) { const float pe = __expf(S[cc][tt][e] - mx); S[cc][tt][e] = pe; den += pe; }
;         den += __shfl_xor(den, 16); den += __shfl_xor(den, 32);
;         const float rden = 1.f / den;
;         bf16x8 pf[8];
; #pragma unroll
;         for (int cc = 0; cc < 8; ++cc) { float t8[8];
; #pragma unroll
;             for (int e = 0; e < 4; ++e) { t8[e] = S[cc][0][e]; t8[4 + e] = S[cc][1][e]; }
;             pf[cc] = pack8(t8); }
; #pragma unroll
;         for (int dt = 0; dt < 8; ++dt) { f32x4 o = (f32x4){0.f, 0.f, 0.f, 0.f};
; #pragma unroll
;             for (int cc = 0; cc < 8; ++cc) { const LAS bf16* vp = Vt + (32 * cc + 4 * kq + (q16 >> 2)) * MEM_VS + 16 * dt + 4 * (q16 & 3);
;                 const v2u lo = vtr(vp), hi = vtr(vp + 16 * MEM_VS);
;                 v4u av; av.x = lo.x; av.y = lo.y; av.z = hi.x; av.w = hi.y;
;                 o = __builtin_amdgcn_mfma_f32_16x16x32_bf16(__builtin_bit_cast(bf16x8, av), pf[cc], o, 0, 0, 0); }
;             if (st) { v2u w; w.x = pk2(o[0] * rden, o[1] * rden); w.y = pk2(o[2] * rden, o[3] * rden);
;                 *(v2u*)(MO + row * 512 + h * 128 + 16 * dt + 4 * kq) = w; } }
	v_sub_f32_e32 v24, v26, v32
	v_add_f32_e32 v69, v29, v69
	v_mul_f32_e32 v24, 0x3fb8aa3b, v24
	v_add_f32_e32 v69, v30, v69
	v_exp_f32_e32 v72, v24
	v_sub_f32_e32 v24, v27, v32
	v_sub_f32_e32 v20, v20, v32
	v_add_f32_e32 v69, v31, v69
	v_mul_f32_e32 v24, 0x3fb8aa3b, v24
	v_mul_f32_e32 v20, 0x3fb8aa3b, v20
	v_exp_f32_e32 v73, v24
	v_add_f32_e32 v24, v70, v69
	v_exp_f32_e32 v69, v20
	v_sub_f32_e32 v20, v21, v32
	v_mul_f32_e32 v20, 0x3fb8aa3b, v20
	v_exp_f32_e32 v74, v20
	v_sub_f32_e32 v20, v22, v32
	v_sub_f32_e32 v16, v16, v32
	v_mul_f32_e32 v20, 0x3fb8aa3b, v20
	v_mul_f32_e32 v16, 0x3fb8aa3b, v16
	v_add_f32_e32 v24, v71, v24
	v_exp_f32_e32 v75, v20
	v_sub_f32_e32 v20, v23, v32
	v_exp_f32_e32 v77, v16
	v_sub_f32_e32 v16, v17, v32
	v_add_f32_e32 v24, v72, v24
	v_mul_f32_e32 v20, 0x3fb8aa3b, v20
	v_mul_f32_e32 v16, 0x3fb8aa3b, v16
	v_add_f32_e32 v24, v73, v24
	v_exp_f32_e32 v76, v20
	v_exp_f32_e32 v78, v16
	v_sub_f32_e32 v16, v18, v32
	v_sub_f32_e32 v12, v12, v32
	v_add_f32_e32 v20, v69, v24
	v_mul_f32_e32 v16, 0x3fb8aa3b, v16
	v_mul_f32_e32 v12, 0x3fb8aa3b, v12
	v_add_f32_e32 v20, v74, v20
	v_exp_f32_e32 v79, v16
	v_sub_f32_e32 v16, v19, v32
	v_exp_f32_e32 v89, v12
	v_sub_f32_e32 v12, v13, v32
	v_add_f32_e32 v20, v75, v20
	v_mul_f32_e32 v16, 0x3fb8aa3b, v16
	v_mul_f32_e32 v12, 0x3fb8aa3b, v12
	v_add_f32_e32 v20, v76, v20
	v_exp_f32_e32 v88, v16
	v_exp_f32_e32 v90, v12
	v_sub_f32_e32 v12, v14, v32
	v_sub_f32_e32 v8, v8, v32
	v_add_f32_e32 v16, v77, v20
	v_mul_f32_e32 v12, 0x3fb8aa3b, v12
	v_mul_f32_e32 v8, 0x3fb8aa3b, v8
	v_add_f32_e32 v16, v78, v16
	v_exp_f32_e32 v91, v12
	v_sub_f32_e32 v12, v15, v32
	v_exp_f32_e32 v93, v8
	v_sub_f32_e32 v8, v9, v32
	v_add_f32_e32 v16, v79, v16
	v_mul_f32_e32 v12, 0x3fb8aa3b, v12
	v_mul_f32_e32 v8, 0x3fb8aa3b, v8
	v_add_f32_e32 v16, v88, v16
	v_exp_f32_e32 v92, v12
	v_exp_f32_e32 v100, v8
	v_sub_f32_e32 v8, v10, v32
	v_sub_f32_e32 v4, v4, v32
	v_add_f32_e32 v12, v89, v16
	v_mul_f32_e32 v8, 0x3fb8aa3b, v8
	v_mul_f32_e32 v4, 0x3fb8aa3b, v4
	v_add_f32_e32 v12, v90, v12
	v_exp_f32_e32 v101, v8
	v_sub_f32_e32 v8, v11, v32
	v_exp_f32_e32 v103, v4
	v_sub_f32_e32 v4, v5, v32
	v_add_f32_e32 v12, v91, v12
	v_mul_f32_e32 v8, 0x3fb8aa3b, v8
	v_mul_f32_e32 v4, 0x3fb8aa3b, v4
	v_add_f32_e32 v12, v92, v12
	v_exp_f32_e32 v102, v8
	v_exp_f32_e32 v104, v4
	v_sub_f32_e32 v4, v6, v32
	v_sub_f32_e32 v0, v0, v32
	v_add_f32_e32 v8, v93, v12
	v_mul_f32_e32 v4, 0x3fb8aa3b, v4
	v_mul_f32_e32 v0, 0x3fb8aa3b, v0
	v_add_f32_e32 v8, v100, v8
	v_exp_f32_e32 v105, v4
	v_sub_f32_e32 v4, v7, v32
	v_exp_f32_e32 v107, v0
	v_sub_f32_e32 v0, v1, v32
	v_add_f32_e32 v8, v101, v8
	v_mul_f32_e32 v4, 0x3fb8aa3b, v4
	v_mul_f32_e32 v0, 0x3fb8aa3b, v0
	v_add_f32_e32 v8, v102, v8
	v_exp_f32_e32 v106, v4
	v_exp_f32_e32 v108, v0
	v_sub_f32_e32 v0, v2, v32
	v_add_f32_e32 v4, v103, v8
	v_mul_f32_e32 v0, 0x3fb8aa3b, v0
	v_add_f32_e32 v4, v104, v4
	v_exp_f32_e32 v109, v0
	v_sub_f32_e32 v0, v3, v32
	v_add_f32_e32 v4, v105, v4
	v_mul_f32_e32 v0, 0x3fb8aa3b, v0
	v_add_f32_e32 v4, v106, v4
	v_exp_f32_e32 v32, v0
	v_add_f32_e32 v0, v107, v4
	v_add_f32_e32 v0, v108, v0
	v_add_f32_e32 v0, v109, v0
	v_add_f32_e32 v0, v32, v0
	ds_bpermute_b32 v1, v38, v0
	v_cvt_pk_bf16_f32 v24, v33, v34
	v_cvt_pk_bf16_f32 v25, v35, v48
	v_cvt_pk_bf16_f32 v26, v49, v50
	v_cvt_pk_bf16_f32 v27, v51, v52
	s_waitcnt lgkmcnt(0)
	v_add_f32_e32 v0, v0, v1
	ds_bpermute_b32 v1, v39, v0
	v_cvt_pk_bf16_f32 v20, v53, v54
	v_cvt_pk_bf16_f32 v21, v55, v56
	v_cvt_pk_bf16_f32 v22, v57, v58
	v_cvt_pk_bf16_f32 v23, v59, v60
	s_waitcnt lgkmcnt(0)
	v_add_f32_e32 v39, v0, v1
	v_cvt_pk_bf16_f32 v16, v61, v62
	v_cvt_pk_bf16_f32 v17, v63, v64
	v_cvt_pk_bf16_f32 v18, v65, v66
	v_cvt_pk_bf16_f32 v19, v67, v68
	v_cvt_pk_bf16_f32 v12, v40, v41
	v_cvt_pk_bf16_f32 v13, v42, v43
	v_cvt_pk_bf16_f32 v14, v44, v45
	v_cvt_pk_bf16_f32 v15, v46, v47
	v_cvt_pk_bf16_f32 v8, v28, v29
	v_cvt_pk_bf16_f32 v9, v30, v31
	v_cvt_pk_bf16_f32 v10, v70, v71
	v_cvt_pk_bf16_f32 v11, v72, v73
	v_cvt_pk_bf16_f32 v4, v69, v74
	v_cvt_pk_bf16_f32 v5, v75, v76
	v_cvt_pk_bf16_f32 v6, v77, v78
	v_cvt_pk_bf16_f32 v7, v79, v88
	v_cvt_pk_bf16_f32 v0, v89, v90
	v_cvt_pk_bf16_f32 v1, v91, v92
	v_cvt_pk_bf16_f32 v2, v93, v100
	v_cvt_pk_bf16_f32 v3, v101, v102
	v_cvt_pk_bf16_f32 v28, v103, v104
	v_cvt_pk_bf16_f32 v29, v105, v106
	v_cvt_pk_bf16_f32 v30, v107, v108
	v_cvt_pk_bf16_f32 v31, v109, v32
	v_lshlrev_b32_e32 v52, 2, v37
	v_lshrrev_b32_e32 v32, 2, v36
	v_add_u32_e32 v32, v32, v52
	v_lshlrev_b32_e32 v33, 3, v36
	v_and_b32_e32 v33, 24, v33
	v_mul_lo_u32 v32, v32, s30
	v_add3_u32 v38, s90, v33, v32
	ds_read_b64_tr_b16 v[194:195], v38
	ds_read_b64_tr_b16 v[196:197], v38 offset:4352
	ds_read_b64_tr_b16 v[198:199], v38 offset:8704
	ds_read_b64_tr_b16 v[200:201], v38 offset:13056
	ds_read_b64_tr_b16 v[202:203], v38 offset:17408
	ds_read_b64_tr_b16 v[204:205], v38 offset:21760
	ds_read_b64_tr_b16 v[206:207], v38 offset:26112
	ds_read_b64_tr_b16 v[208:209], v38 offset:30464
	ds_read_b64_tr_b16 v[210:211], v38 offset:34816
	ds_read_b64_tr_b16 v[212:213], v38 offset:39168
	s_nop 3
	s_waitcnt lgkmcnt(8)
	v_mfma_f32_16x16x32_bf16 v[32:35], v[194:197], v[24:27], 0
	s_nop 3
	v_div_scale_f32 v53, s[2:3], v39, v39, 1.0
	s_waitcnt lgkmcnt(6)
	v_mfma_f32_16x16x32_bf16 v[32:35], v[198:201], v[20:23], v[32:35]
	s_nop 1
	v_rcp_f32_e32 v37, v53
	s_add_u32 s2, s28, s0
	s_waitcnt lgkmcnt(4)
	v_mfma_f32_16x16x32_bf16 v[32:35], v[202:205], v[16:19], v[32:35]
	ds_read_b64_tr_b16 v[44:45], v38 offset:43520
	ds_read_b64_tr_b16 v[46:47], v38 offset:47872
	v_cmp_gt_i32_e64 s[0:1], 8, v36
	v_fma_f32 v36, -v53, v37, 1.0
	s_waitcnt lgkmcnt(4)
	v_mfma_f32_16x16x32_bf16 v[32:35], v[206:209], v[12:15], v[32:35]
	ds_read_b64_tr_b16 v[48:49], v38 offset:52224
	ds_read_b64_tr_b16 v[50:51], v38 offset:56576
	v_fmac_f32_e32 v37, v36, v37
	v_div_scale_f32 v36, vcc, 1.0, v39, 1.0
	s_waitcnt lgkmcnt(4)
	v_mfma_f32_16x16x32_bf16 v[32:35], v[210:213], v[8:11], v[32:35]
	ds_read_b64_tr_b16 v[40:41], v38 offset:60928
	ds_read_b64_tr_b16 v[42:43], v38 offset:65280
	v_mul_f32_e32 v54, v36, v37
	v_fma_f32 v55, -v53, v54, v36
	s_waitcnt lgkmcnt(4)
	v_mfma_f32_16x16x32_bf16 v[32:35], v[44:47], v[4:7], v[32:35]
	v_fmac_f32_e32 v54, v55, v37
	v_fma_f32 v36, -v53, v54, v36
	s_addc_u32 s3, s29, 0
	s_waitcnt lgkmcnt(2)
	v_mfma_f32_16x16x32_bf16 v[32:35], v[48:51], v[0:3], v[32:35]
	v_div_fmas_f32 v36, v36, v37, v54
	v_div_fixup_f32 v39, v36, v39, 1.0
	v_lshl_add_u64 v[36:37], s[2:3], 0, v[82:83]
	s_waitcnt lgkmcnt(0)
	v_mfma_f32_16x16x32_bf16 v[32:35], v[40:43], v[28:31], v[32:35]
	v_ashrrev_i32_e32 v53, 31, v52
	v_lshl_add_u64 v[36:37], v[52:53], 1, v[36:37]
	s_and_saveexec_b64 s[2:3], s[0:1]
	s_cbranch_execz .LBB0_603
	s_nop 3
	v_mul_f32_e32 v32, v32, v39
	v_mul_f32_e32 v33, v33, v39
	v_cvt_pk_bf16_f32 v32, v32, v33
	v_mul_f32_e32 v33, v34, v39
	v_mul_f32_e32 v34, v35, v39
	v_cvt_pk_bf16_f32 v33, v33, v34
	global_store_dwordx2 v[36:37], v[32:33], off

; template <bool SAMPLE>
; __device__ __forceinline__ void mem_unit(const Params& p, int l, LAS unsigned char* lds, int unit, int tid, int wave, int lane) {
;     ...
;       }
;     }
;     __syncthreads();
.LBB0_618:
	s_nop 0
	s_nop 0
	s_nop 0
	s_nop 0
	s_nop 0
	s_nop 0
	s_nop 0
	s_nop 0
	s_nop 0
	s_nop 0
	s_nop 0
	s_nop 0
	s_nop 0
	s_nop 0
	s_nop 0
	s_nop 0
	s_nop 0
	s_nop 0
	s_nop 0
	s_nop 0
	s_nop 0
	s_nop 0
	s_nop 0
	s_nop 0
	s_mov_b64 s[0:1], 0
	s_barrier

; template <bool SAMPLE>
; __device__ __forceinline__ void mem_unit(const Params& p, int l, LAS unsigned char* lds, int unit, int tid, int wave, int lane) {
;     ...
;         for (int hb = 0; hb < 2; ++hb) {
;             float kk[4][8], vv[4][8];
; #pragma unroll
;             for (int it = 0; it < 4; ++it) { const int s = (tid >> 4) + 32 * (4 * hb + it);
;                 const float* kp; const float* vp;
;                 if (!SAMPLE) { kp = (const float*)(p.ws + W_MKV) + ((size_t)l * 1024 + b * 256 + s) * 1024 + h * 128 + sub * 8; vp = kp + 512; }
;                 else { const size_t o = ((((size_t)l * 128 + b) * 256 + s) * 4 + h) * 128 + sub * 8; kp = p.in[I_CMK] + o; vp = p.in[I_CMV] + o; }
;                 if (SAMPLE) { pg8::ld8f_nt(kp, kk[it]); pg8::ld8f_nt(vp, vv[it]); } else { pg8::ld8f(kp, kk[it]); pg8::ld8f(vp, vv[it]); } }
.LBB0_2730:
	v_add_u32_e32 v66, s8, v81
	v_ashrrev_i32_e32 v67, 31, v66
	v_add_u32_e32 v6, 0x60, v66
	v_lshl_add_u64 v[8:9], v[66:67], 0, s[10:11]
	v_add_u32_e32 v2, 32, v66
	v_add_u32_e32 v4, 64, v66
	v_ashrrev_i32_e32 v7, 31, v6
	v_lshlrev_b64 v[8:9], 11, v[8:9]
	v_ashrrev_i32_e32 v3, 31, v2
	v_ashrrev_i32_e32 v5, 31, v4
	v_lshl_add_u64 v[6:7], v[6:7], 0, s[10:11]
	v_or_b32_e32 v8, v8, v0
	v_lshl_add_u64 v[2:3], v[2:3], 0, s[10:11]
	v_lshl_add_u64 v[4:5], v[4:5], 0, s[10:11]
	v_lshlrev_b64 v[22:23], 11, v[6:7]
	v_lshl_add_u64 v[6:7], s[78:79], 0, v[8:9]
	v_lshl_add_u64 v[14:15], s[80:81], 0, v[8:9]
	v_lshlrev_b64 v[18:19], 11, v[2:3]
	v_lshlrev_b64 v[20:21], 11, v[4:5]
	s_cmp_lg_u32 s8, 0
	s_cbranch_scc1 .Lp6s_it1_1
	s_mov_b32 s100, 0x40000
	s_mov_b32 s101, 0
	v_lshl_add_u64 v[6:7], v[6:7], 0, s[100:101]
	v_lshl_add_u64 v[14:15], v[14:15], 0, s[100:101]
	global_load_dwordx4 v[186:189], v[6:7], off nt
	s_nop 0
	global_load_dwordx4 v[190:193], v[6:7], off offset:16 nt
	s_nop 0
	global_load_dwordx4 v[194:197], v[14:15], off offset:16 nt
	s_nop 0
	global_load_dwordx4 v[198:201], v[14:15], off nt
	s_nop 0
	s_mov_b32 s100, 0xfffc0000
	s_mov_b32 s101, -1
	v_lshl_add_u64 v[6:7], v[6:7], 0, s[100:101]
	v_lshl_add_u64 v[14:15], v[14:15], 0, s[100:101]
	global_load_dwordx4 v[2:5], v[6:7], off nt
	s_nop 0
	global_load_dwordx4 v[6:9], v[6:7], off offset:16 nt
	s_nop 0
	global_load_dwordx4 v[10:13], v[14:15], off offset:16 nt
	s_nop 0
	global_load_dwordx4 v[14:17], v[14:15], off nt
	v_or_b32_e32 v18, v18, v0
	v_or_b32_e32 v20, v20, v0
	v_or_b32_e32 v22, v22, v0
	v_lshl_add_u64 v[24:25], s[78:79], 0, v[18:19]
	v_lshl_add_u64 v[30:31], s[80:81], 0, v[18:19]
	v_lshl_add_u64 v[38:39], s[78:79], 0, v[20:21]
	v_lshl_add_u64 v[46:47], s[80:81], 0, v[20:21]
	v_lshl_add_u64 v[54:55], s[78:79], 0, v[22:23]
	v_lshl_add_u64 v[62:63], s[80:81], 0, v[22:23]
	s_mov_b32 s100, 0x40000
	s_mov_b32 s101, 0
	v_lshl_add_u64 v[24:25], v[24:25], 0, s[100:101]
	v_lshl_add_u64 v[30:31], v[30:31], 0, s[100:101]
	v_lshl_add_u64 v[38:39], v[38:39], 0, s[100:101]
	v_lshl_add_u64 v[46:47], v[46:47], 0, s[100:101]
	v_lshl_add_u64 v[54:55], v[54:55], 0, s[100:101]
	v_lshl_add_u64 v[62:63], v[62:63], 0, s[100:101]
	global_load_dwordx4 v[202:205], v[24:25], off nt
	s_nop 0
	global_load_dwordx4 v[206:209], v[24:25], off offset:16 nt
	s_nop 0
	global_load_dwordx4 v[210:213], v[30:31], off nt
	s_nop 0
	global_load_dwordx4 v[218:221], v[30:31], off offset:16 nt
	s_nop 0
	global_load_dwordx4 v[222:225], v[38:39], off nt
	s_nop 0
	global_load_dwordx4 v[226:229], v[38:39], off offset:16 nt
	s_nop 0
	global_load_dwordx4 v[230:233], v[46:47], off nt
	s_nop 0
	global_load_dwordx4 v[234:237], v[46:47], off offset:16 nt
	s_nop 0
	global_load_dwordx4 v[242:245], v[54:55], off nt
	s_nop 0
	global_load_dwordx4 v[246:249], v[54:55], off offset:16 nt
	s_nop 0
	global_load_dwordx4 v[250:253], v[62:63], off nt
	s_nop 0
	global_load_dwordx2 v[214:215], v[62:63], off offset:16 nt
	global_load_dwordx2 v[254:255], v[62:63], off offset:24 nt
	s_nop 0
	s_mov_b32 s100, 0xfffc0000
	s_mov_b32 s101, -1
	v_lshl_add_u64 v[24:25], v[24:25], 0, s[100:101]
	v_lshl_add_u64 v[30:31], v[30:31], 0, s[100:101]
	v_lshl_add_u64 v[38:39], v[38:39], 0, s[100:101]
	v_lshl_add_u64 v[46:47], v[46:47], 0, s[100:101]
	v_lshl_add_u64 v[54:55], v[54:55], 0, s[100:101]
	v_lshl_add_u64 v[62:63], v[62:63], 0, s[100:101]
	global_load_dwordx4 v[18:21], v[24:25], off nt
	s_nop 0
	global_load_dwordx4 v[22:25], v[24:25], off offset:16 nt
	s_nop 0
	global_load_dwordx4 v[26:29], v[30:31], off nt
	s_nop 0
	global_load_dwordx4 v[30:33], v[30:31], off offset:16 nt
	s_nop 0
	global_load_dwordx4 v[34:37], v[38:39], off nt
	s_nop 0
	global_load_dwordx4 v[38:41], v[38:39], off offset:16 nt
	s_nop 0
	global_load_dwordx4 v[42:45], v[46:47], off nt
	s_nop 0
	global_load_dwordx4 v[46:49], v[46:47], off offset:16 nt
	s_nop 0
	global_load_dwordx4 v[50:53], v[54:55], off nt
	s_nop 0
	global_load_dwordx4 v[54:57], v[54:55], off offset:16 nt
	s_nop 0
	global_load_dwordx4 v[58:61], v[62:63], off nt
	s_nop 0
	global_load_dwordx4 v[62:65], v[62:63], off offset:16 nt
	s_branch .Lp6s_join_1

; #define LAS __attribute__((address_space(3)))
; __device__ __forceinline__ void unpack8(const v4u w, float (&o)[8]) { o[0] = bflo(w.x); o[1] = bfhi(w.x); o[2] = bflo(w.y); o[3] = bfhi(w.y); o[4] = bflo(w.z); o[5] = bfhi(w.z); o[6] = bflo(w.w); o[7] = bfhi(w.w); }
; __device__ __forceinline__ bf16x8 pack8(const float (&o)[8]) { v4u w; w.x = pk2(o[0], o[1]); w.y = pk2(o[2], o[3]); w.z = pk2(o[4], o[5]); w.w = pk2(o[6], o[7]); return __builtin_bit_cast(bf16x8, w); }
; template <bool SAMPLE>
; __device__ __forceinline__ void mem_unit(const Params& p, int l, LAS unsigned char* lds, int unit, int tid, int wave, int lane) {
;     ...
;                 *(LAS bf16x8*)(Kl + s * MEM_KS + sub * 8) = pack8(k);
;                 *(LAS bf16x8*)(Vt + s * MEM_VS + sub * 8) = pack8(v);
;             }
;         }
;     }
;     __syncthreads();
;     if (!SAMPLE || wave == 0) {
; #pragma unroll 1
;       for (int qq = 0; qq < (SAMPLE ? 1 : 4); ++qq) {
;         int q16 = lane & 15, kq = lane >> 4; asm volatile("" : "+v"(q16), "+v"(kq));
;         size_t row; bool st;
;         if (!SAMPLE) { row = (size_t)b * 8192 + (qt * 4 + qq) * 128 + 16 * wave + q16; st = true; } else { row = (size_t)MP + 8 * b + (q16 & 7); st = q16 < 8; }
;         bf16x8 qf[4];
;         {
;             float qv[4][8]; float ss = 0.f;
; #pragma unroll
;             for (int dc = 0; dc < 4; ++dc) { unpack8(*(const v4u*)(MQ + row * 512 + h * 128 + 32 * dc + 8 * kq), qv[dc]);
; #pragma unroll
;                 for (int e = 0; e < 8; ++e) ss += qv[dc][e] * qv[dc][e]; }
;             ss += __shfl_xor(ss, 16); ss += __shfl_xor(ss, 32);
;             const float rs = rsqrtf(ss * (1.f / 128.f) + EPS) * 0.08838834764831845f;
.Lp6s_join_1:
	v_cndmask_b32_e64 v1, 0, 1, s[0:1]
	v_cmp_ne_u32_e32 vcc, 1, v1
	v_mul_lo_u32 v1, v66, s22
	v_add_u32_e32 v66, v96, v1
	v_add_u32_e32 v1, v97, v1
	s_movk_i32 s8, 0x80
	s_mov_b64 s[0:1], 0
	s_and_b64 vcc, exec, vcc
	s_waitcnt vmcnt(28)
	v_cvt_pk_bf16_f32 v2, v2, v3
	v_cvt_pk_bf16_f32 v3, v4, v5
	s_waitcnt vmcnt(27)
	v_cvt_pk_bf16_f32 v4, v6, v7
	v_cvt_pk_bf16_f32 v5, v8, v9
	ds_write_b128 v66, v[2:5]
	s_waitcnt vmcnt(25)
	v_cvt_pk_bf16_f32 v2, v14, v15
	v_cvt_pk_bf16_f32 v3, v16, v17
	v_cvt_pk_bf16_f32 v4, v10, v11
	v_cvt_pk_bf16_f32 v5, v12, v13
	ds_write_b128 v1, v[2:5]
	s_waitcnt vmcnt(11)
	v_cvt_pk_bf16_f32 v2, v18, v19
	v_cvt_pk_bf16_f32 v3, v20, v21
	s_waitcnt vmcnt(10)
	v_cvt_pk_bf16_f32 v4, v22, v23
	v_cvt_pk_bf16_f32 v5, v24, v25
	ds_write_b128 v66, v[2:5] offset:8704
	s_waitcnt vmcnt(9)
	v_cvt_pk_bf16_f32 v2, v26, v27
	v_cvt_pk_bf16_f32 v3, v28, v29
	s_waitcnt vmcnt(8)
	v_cvt_pk_bf16_f32 v4, v30, v31
	v_cvt_pk_bf16_f32 v5, v32, v33
	ds_write_b128 v1, v[2:5] offset:8704
	s_waitcnt vmcnt(7)
	v_cvt_pk_bf16_f32 v2, v34, v35
	v_cvt_pk_bf16_f32 v3, v36, v37
	s_waitcnt vmcnt(6)
	v_cvt_pk_bf16_f32 v4, v38, v39
	v_cvt_pk_bf16_f32 v5, v40, v41
	ds_write_b128 v66, v[2:5] offset:17408
	s_waitcnt vmcnt(5)
	v_cvt_pk_bf16_f32 v2, v42, v43
	v_cvt_pk_bf16_f32 v3, v44, v45
	s_waitcnt vmcnt(4)
	v_cvt_pk_bf16_f32 v4, v46, v47
	v_cvt_pk_bf16_f32 v5, v48, v49
	ds_write_b128 v1, v[2:5] offset:17408
	s_waitcnt vmcnt(3)
	v_cvt_pk_bf16_f32 v2, v50, v51
	v_cvt_pk_bf16_f32 v3, v52, v53
	s_waitcnt vmcnt(2)
	v_cvt_pk_bf16_f32 v4, v54, v55
	v_cvt_pk_bf16_f32 v5, v56, v57
	ds_write_b128 v66, v[2:5] offset:26112
	s_waitcnt vmcnt(1)
	v_cvt_pk_bf16_f32 v2, v58, v59
	v_cvt_pk_bf16_f32 v3, v60, v61
	s_waitcnt vmcnt(0)
	v_cvt_pk_bf16_f32 v4, v62, v63
	v_cvt_pk_bf16_f32 v5, v64, v65
	ds_write_b128 v1, v[2:5] offset:26112
	s_cbranch_vccz .LBB0_2730
	s_andn2_b64 vcc, exec, s[6:7]
	s_waitcnt lgkmcnt(0)
	s_barrier
	s_cbranch_vccnz .LBB0_2749
	s_lshl_b32 s0, s2, 3
	s_add_i32 s1, s0, 0x8000
	s_lshl_b32 s0, s3, 1
	v_mov_b32_e32 v37, v95
	v_mov_b32_e32 v36, v94
	s_add_u32 s2, s64, s0
	s_addc_u32 s3, s65, 0
	v_and_or_b32 v0, v36, 7, s1
	v_lshlrev_b32_e32 v82, 10, v0
	v_lshlrev_b32_e32 v16, 3, v37
	v_lshl_add_u64 v[0:1], s[2:3], 0, v[82:83]
	v_ashrrev_i32_e32 v17, 31, v16
	v_lshl_add_u64 v[12:13], v[16:17], 1, v[0:1]
	global_load_dwordx4 v[0:3], v[12:13], off
	global_load_dwordx4 v[4:7], v[12:13], off offset:64
	global_load_dwordx4 v[8:11], v[12:13], off offset:128
	s_nop 0
	global_load_dwordx4 v[12:15], v[12:13], off offset:192
	v_and_b32_e32 v19, 64, v99
	v_xor_b32_e32 v18, 16, v99
	v_add_u32_e32 v34, 64, v19
	v_cmp_lt_i32_e32 vcc, v18, v34
	v_lshl_add_u64 v[24:25], v[16:17], 2, s[46:47]
	s_waitcnt vmcnt(3)
	v_and_b32_e32 v40, 0xffff0000, v0
	v_cndmask_b32_e32 v18, v99, v18, vcc
	v_lshlrev_b32_e32 v38, 2, v18
	global_load_dwordx4 v[16:19], v[24:25], off offset:528
	global_load_dwordx4 v[20:23], v[24:25], off offset:512
	v_lshlrev_b32_e32 v35, 16, v0
	s_waitcnt vmcnt(3)
	v_lshlrev_b32_e32 v55, 16, v8
	v_and_b32_e32 v56, 0xffff0000, v8
	v_mul_f32_e32 v8, v40, v40
	v_lshlrev_b32_e32 v41, 16, v1
	v_fmac_f32_e32 v8, v35, v35
	v_and_b32_e32 v42, 0xffff0000, v1
	v_fmac_f32_e32 v8, v41, v41
	v_lshlrev_b32_e32 v43, 16, v2
	v_fmac_f32_e32 v8, v42, v42
	v_and_b32_e32 v44, 0xffff0000, v2
	v_fmac_f32_e32 v8, v43, v43
	v_lshlrev_b32_e32 v45, 16, v3
	v_fmac_f32_e32 v8, v44, v44
	v_and_b32_e32 v46, 0xffff0000, v3
	v_fmac_f32_e32 v8, v45, v45
	v_lshlrev_b32_e32 v47, 16, v4
	v_fmac_f32_e32 v8, v46, v46
	v_and_b32_e32 v48, 0xffff0000, v4
	v_fmac_f32_e32 v8, v47, v47
	v_lshlrev_b32_e32 v49, 16, v5
	v_fmac_f32_e32 v8, v48, v48
	v_and_b32_e32 v50, 0xffff0000, v5
	v_fmac_f32_e32 v8, v49, v49
	v_lshlrev_b32_e32 v51, 16, v6
	v_fmac_f32_e32 v8, v50, v50
	v_and_b32_e32 v52, 0xffff0000, v6
	v_fmac_f32_e32 v8, v51, v51
	v_lshlrev_b32_e32 v53, 16, v7
	v_fmac_f32_e32 v8, v52, v52
	v_and_b32_e32 v54, 0xffff0000, v7
	v_fmac_f32_e32 v8, v53, v53
	v_fmac_f32_e32 v8, v54, v54
	v_fmac_f32_e32 v8, v55, v55
	v_lshlrev_b32_e32 v57, 16, v9
	v_fmac_f32_e32 v8, v56, v56
	v_and_b32_e32 v58, 0xffff0000, v9
	v_fmac_f32_e32 v8, v57, v57
	v_lshlrev_b32_e32 v59, 16, v10
	v_fmac_f32_e32 v8, v58, v58
	v_and_b32_e32 v60, 0xffff0000, v10
	v_fmac_f32_e32 v8, v59, v59
	v_lshlrev_b32_e32 v61, 16, v11
	v_fmac_f32_e32 v8, v60, v60
	v_and_b32_e32 v62, 0xffff0000, v11
	s_waitcnt vmcnt(2)
	v_and_b32_e32 v26, 0xffff0000, v12
	v_lshlrev_b32_e32 v27, 16, v12
	v_fmac_f32_e32 v8, v61, v61
	v_pk_mul_f32 v[0:1], v[26:27], v[26:27]
	v_fmac_f32_e32 v8, v62, v62
	v_and_b32_e32 v28, 0xffff0000, v13
	v_lshlrev_b32_e32 v29, 16, v13
	v_add_f32_e32 v1, v1, v8
	v_pk_mul_f32 v[2:3], v[28:29], v[28:29]
	v_add_f32_e32 v0, v0, v1
	v_and_b32_e32 v30, 0xffff0000, v14
	v_lshlrev_b32_e32 v31, 16, v14
	v_add_f32_e32 v0, v3, v0
	v_pk_mul_f32 v[4:5], v[30:31], v[30:31]
	v_add_f32_e32 v0, v2, v0
	v_and_b32_e32 v32, 0xffff0000, v15
	v_lshlrev_b32_e32 v33, 16, v15
	v_add_f32_e32 v0, v5, v0
	v_pk_mul_f32 v[6:7], v[32:33], v[32:33]
	v_add_f32_e32 v0, v4, v0
	v_add_f32_e32 v0, v7, v0
	v_add_f32_e32 v0, v6, v0
	ds_bpermute_b32 v1, v38, v0
	v_xor_b32_e32 v2, 32, v99
	v_cmp_lt_i32_e32 vcc, v2, v34
	s_waitcnt lgkmcnt(0)
	v_add_f32_e32 v0, v0, v1
	v_cndmask_b32_e32 v2, v99, v2, vcc
	v_lshlrev_b32_e32 v39, 2, v2
	ds_bpermute_b32 v1, v39, v0
	s_waitcnt lgkmcnt(0)
	v_add_f32_e32 v0, v0, v1
	v_fmamk_f32 v0, v0, 0x3c000000, v98
	v_mul_f32_e32 v1, 0x4b800000, v0
	v_cmp_gt_f32_e32 vcc, s23, v0
	s_nop 1
	v_cndmask_b32_e32 v0, v0, v1, vcc
	v_rsq_f32_e32 v0, v0
	s_nop 0
	v_mul_f32_e32 v1, 0x45800000, v0
	v_cndmask_b32_e32 v0, v0, v1, vcc
	v_mul_f32_e32 v34, 0x3db504f3, v0
	s_waitcnt vmcnt(0)
; #define LAS __attribute__((address_space(3)))
; __device__ __forceinline__ bf16x8 pack8(const float (&o)[8]) { v4u w; w.x = pk2(o[0], o[1]); w.y = pk2(o[2], o[3]); w.z = pk2(o[4], o[5]); w.w = pk2(o[6], o[7]); return __builtin_bit_cast(bf16x8, w); }
; template <bool SAMPLE>
; __device__ __forceinline__ void mem_unit(const Params& p, int l, LAS unsigned char* lds, int unit, int tid, int wave, int lane) {
;     ...
; #pragma unroll
;             for (int dc = 0; dc < 4; ++dc) { float qg[8]; pg8::ld8f(p.in[I_MQG] + l * 128 + 32 * dc + 8 * kq, qg);
; #pragma unroll
;                 for (int e = 0; e < 8; ++e) qv[dc][e] *= rs * qg[e];
;                 qf[dc] = pack8(qv[dc]); }
;         }
;         f32x4 S[8][2]; float mx = -INFINITY;
; #pragma unroll
;         for (int cc = 0; cc < 8; ++cc)
; #pragma unroll
;             for (int tt = 0; tt < 2; ++tt) { const int kb = 32 * cc + 16 * tt; f32x4 a = (f32x4){0.f, 0.f, 0.f, 0.f};
; #pragma unroll
;                 for (int dc = 0; dc < 4; ++dc) { const bf16x8 kf = *(const LAS bf16x8*)(Kl + (kb + q16) * MEM_KS + 32 * dc + 8 * kq);
;                     a = __builtin_amdgcn_mfma_f32_16x16x32_bf16(kf, qf[dc], a, 0, 0, 0); }
	v_mul_f32_e32 v0, v20, v34
	v_mul_f32_e32 v1, v21, v34
	v_mul_f32_e32 v2, v22, v34
	v_mul_f32_e32 v3, v23, v34
	v_mul_f32_e32 v4, v16, v34
	v_mul_f32_e32 v5, v17, v34
	v_mul_f32_e32 v6, v18, v34
	v_mul_f32_e32 v7, v19, v34
	v_mul_f32_e32 v0, v0, v35
	v_mul_f32_e32 v1, v1, v40
	v_mul_f32_e32 v2, v2, v41
	v_mul_f32_e32 v3, v3, v42
	v_mul_f32_e32 v4, v4, v43
	v_mul_f32_e32 v5, v5, v44
	v_mul_f32_e32 v6, v6, v45
	v_mul_f32_e32 v7, v7, v46
	v_cvt_pk_bf16_f32 v0, v0, v1
	v_cvt_pk_bf16_f32 v1, v2, v3
	v_cvt_pk_bf16_f32 v2, v4, v5
	v_cvt_pk_bf16_f32 v3, v6, v7
	global_load_dwordx4 v[4:7], v[24:25], off offset:640
	global_load_dwordx4 v[8:11], v[24:25], off offset:656
	v_lshlrev_b32_e32 v20, 4, v37
	v_mul_lo_u32 v21, v36, s22
	v_add3_u32 v92, 0, v20, v21
	s_waitcnt vmcnt(1)
	v_mul_f32_e32 v4, v4, v34
	v_mul_f32_e32 v5, v5, v34
	v_mul_f32_e32 v6, v6, v34
	v_mul_f32_e32 v7, v7, v34
	s_waitcnt vmcnt(0)
	v_mul_f32_e32 v8, v8, v34
	v_mul_f32_e32 v9, v9, v34
	v_mul_f32_e32 v10, v10, v34
	v_mul_f32_e32 v11, v11, v34
	v_mul_f32_e32 v4, v4, v47
	v_mul_f32_e32 v5, v5, v48
	v_mul_f32_e32 v6, v6, v49
	v_mul_f32_e32 v7, v7, v50
	v_mul_f32_e32 v12, v8, v51
	v_mul_f32_e32 v13, v9, v52
	v_mul_f32_e32 v14, v10, v53
	v_mul_f32_e32 v11, v11, v54
	v_cvt_pk_bf16_f32 v8, v4, v5
	v_cvt_pk_bf16_f32 v9, v6, v7
	v_cvt_pk_bf16_f32 v10, v12, v13
	v_cvt_pk_bf16_f32 v11, v14, v11
	global_load_dwordx4 v[4:7], v[24:25], off offset:768
	global_load_dwordx4 v[12:15], v[24:25], off offset:784
	s_waitcnt vmcnt(1)
	v_mul_f32_e32 v4, v4, v34
	v_mul_f32_e32 v5, v5, v34
	v_mul_f32_e32 v6, v6, v34
	v_mul_f32_e32 v7, v7, v34
	s_waitcnt vmcnt(0)
	v_mul_f32_e32 v12, v12, v34
	v_mul_f32_e32 v13, v13, v34
	v_mul_f32_e32 v14, v14, v34
	v_mul_f32_e32 v15, v15, v34
	v_mul_f32_e32 v4, v4, v55
	v_mul_f32_e32 v5, v5, v56
	v_mul_f32_e32 v6, v6, v57
	v_mul_f32_e32 v7, v7, v58
	v_mul_f32_e32 v12, v12, v59
	v_mul_f32_e32 v13, v13, v60
	v_mul_f32_e32 v14, v14, v61
	v_mul_f32_e32 v15, v15, v62
	v_cvt_pk_bf16_f32 v4, v4, v5
	v_cvt_pk_bf16_f32 v5, v6, v7
	v_cvt_pk_bf16_f32 v6, v12, v13
	v_cvt_pk_bf16_f32 v7, v14, v15
	global_load_dwordx4 v[12:15], v[24:25], off offset:896
	global_load_dwordx4 v[16:19], v[24:25], off offset:912
	s_waitcnt vmcnt(1)
	v_mul_f32_e32 v12, v12, v34
	v_mul_f32_e32 v13, v13, v34
	v_mul_f32_e32 v14, v14, v34
	v_mul_f32_e32 v15, v15, v34
	s_waitcnt vmcnt(0)
	v_mul_f32_e32 v16, v16, v34
	v_mul_f32_e32 v17, v17, v34
	v_mul_f32_e32 v18, v18, v34
	v_mul_f32_e32 v19, v19, v34
	v_mul_f32_e32 v12, v12, v27
	v_mul_f32_e32 v13, v13, v26
	v_mul_f32_e32 v14, v14, v29
	v_mul_f32_e32 v15, v15, v28
	v_mul_f32_e32 v16, v16, v31
	v_mul_f32_e32 v17, v17, v30
	v_mul_f32_e32 v18, v18, v33
	v_mul_f32_e32 v19, v19, v32
	v_cvt_pk_bf16_f32 v32, v12, v13
	v_cvt_pk_bf16_f32 v33, v14, v15
	v_cvt_pk_bf16_f32 v34, v16, v17
	v_cvt_pk_bf16_f32 v35, v18, v19
	ds_read_b128 v[186:189], v92
	ds_read_b128 v[190:193], v92 offset:4352
	ds_read_b128 v[194:197], v92 offset:8704
	ds_read_b128 v[198:201], v92 offset:13056
	ds_read_b128 v[202:205], v92 offset:17408
	s_nop 0
	ds_read_b128 v[16:19], v92 offset:64
	s_nop 0
	ds_read_b128 v[24:27], v92 offset:4416
	s_nop 0
	ds_read_b128 v[40:43], v92 offset:8768
	s_nop 0
	ds_read_b128 v[48:51], v92 offset:13120
	s_nop 0
	ds_read_b128 v[56:59], v92 offset:17472
	ds_read_b128 v[60:63], v92 offset:21760
	ds_read_b128 v[64:67], v92 offset:21824
	ds_read_b128 v[68:71], v92 offset:26112
	ds_read_b128 v[72:75], v92 offset:26176
	ds_read_b128 v[76:79], v92 offset:30464
	ds_read_b128 v[88:91], v92 offset:30528
	ds_read_b128 v[100:103], v92 offset:34816
	ds_read_b128 v[104:107], v92 offset:34880
	ds_read_b128 v[108:111], v92 offset:39168
	ds_read_b128 v[112:115], v92 offset:39232
	ds_read_b128 v[116:119], v92 offset:43520
	ds_read_b128 v[120:123], v92 offset:43584
	ds_read_b128 v[124:127], v92 offset:47872
	ds_read_b128 v[128:131], v92 offset:47936
	ds_read_b128 v[132:135], v92 offset:52224
	ds_read_b128 v[136:139], v92 offset:52288
	ds_read_b128 v[140:143], v92 offset:56576
	ds_read_b128 v[144:147], v92 offset:56640
	ds_read_b128 v[148:151], v92 offset:60928
	ds_read_b128 v[152:155], v92 offset:60992
	ds_read_b128 v[156:159], v92 offset:65280
	ds_read_b128 v[160:163], v92 offset:65344
	s_waitcnt lgkmcnt(14)
	v_mfma_f32_16x16x32_bf16 v[12:15], v[186:189], v[0:3], 0
	v_mfma_f32_16x16x32_bf16 v[20:23], v[190:193], v[0:3], 0
	v_mfma_f32_16x16x32_bf16 v[28:31], v[194:197], v[0:3], 0
	v_mfma_f32_16x16x32_bf16 v[44:47], v[198:201], v[0:3], 0
	v_mfma_f32_16x16x32_bf16 v[52:55], v[202:205], v[0:3], 0
	v_mfma_f32_16x16x32_bf16 v[60:63], v[60:63], v[0:3], 0
	v_mfma_f32_16x16x32_bf16 v[68:71], v[68:71], v[0:3], 0
	v_mfma_f32_16x16x32_bf16 v[76:79], v[76:79], v[0:3], 0
	v_mfma_f32_16x16x32_bf16 v[100:103], v[100:103], v[0:3], 0
	s_waitcnt lgkmcnt(13)
	v_mfma_f32_16x16x32_bf16 v[108:111], v[108:111], v[0:3], 0
	s_waitcnt lgkmcnt(11)
	v_mfma_f32_16x16x32_bf16 v[116:119], v[116:119], v[0:3], 0
	s_waitcnt lgkmcnt(9)
	v_mfma_f32_16x16x32_bf16 v[124:127], v[124:127], v[0:3], 0
	s_waitcnt lgkmcnt(7)
	v_mfma_f32_16x16x32_bf16 v[132:135], v[132:135], v[0:3], 0
	s_waitcnt lgkmcnt(5)
	v_mfma_f32_16x16x32_bf16 v[140:143], v[140:143], v[0:3], 0
	s_waitcnt lgkmcnt(3)
	v_mfma_f32_16x16x32_bf16 v[148:151], v[148:151], v[0:3], 0
	s_waitcnt lgkmcnt(1)
; #define LAS __attribute__((address_space(3)))
; template <bool SAMPLE>
; __device__ __forceinline__ void mem_unit(const Params& p, int l, LAS unsigned char* lds, int unit, int tid, int wave, int lane) {
;     ...
;         for (int cc = 0; cc < 8; ++cc)
; #pragma unroll
;             for (int tt = 0; tt < 2; ++tt) { const int kb = 32 * cc + 16 * tt; f32x4 a = (f32x4){0.f, 0.f, 0.f, 0.f};
; #pragma unroll
;                 for (int dc = 0; dc < 4; ++dc) { const bf16x8 kf = *(const LAS bf16x8*)(Kl + (kb + q16) * MEM_KS + 32 * dc + 8 * kq);
;                     a = __builtin_amdgcn_mfma_f32_16x16x32_bf16(kf, qf[dc], a, 0, 0, 0); }
; #pragma unroll
;                 for (int e = 0; e < 4; ++e) mx = fmaxf(mx, a[e]);
;                 S[cc][tt] = a; }
	v_mfma_f32_16x16x32_bf16 v[0:3], v[156:159], v[0:3], 0
	v_mfma_f32_16x16x32_bf16 v[12:15], v[16:19], v[8:11], v[12:15]
	v_mfma_f32_16x16x32_bf16 v[16:19], v[24:27], v[8:11], v[20:23]
	v_mfma_f32_16x16x32_bf16 v[20:23], v[40:43], v[8:11], v[28:31]
	v_mfma_f32_16x16x32_bf16 v[24:27], v[48:51], v[8:11], v[44:47]
	v_mfma_f32_16x16x32_bf16 v[28:31], v[56:59], v[8:11], v[52:55]
	v_mfma_f32_16x16x32_bf16 v[40:43], v[64:67], v[8:11], v[60:63]
	v_mfma_f32_16x16x32_bf16 v[44:47], v[72:75], v[8:11], v[68:71]
	v_mfma_f32_16x16x32_bf16 v[48:51], v[88:91], v[8:11], v[76:79]
	v_mfma_f32_16x16x32_bf16 v[52:55], v[104:107], v[8:11], v[100:103]
	ds_read_b128 v[190:193], v92 offset:128
	ds_read_b128 v[194:197], v92 offset:4480
	ds_read_b128 v[198:201], v92 offset:8832
	ds_read_b128 v[202:205], v92 offset:13184
	v_mfma_f32_16x16x32_bf16 v[56:59], v[112:115], v[8:11], v[108:111]
	v_mfma_f32_16x16x32_bf16 v[60:63], v[120:123], v[8:11], v[116:119]
	v_mfma_f32_16x16x32_bf16 v[64:67], v[128:131], v[8:11], v[124:127]
	v_mfma_f32_16x16x32_bf16 v[68:71], v[136:139], v[8:11], v[132:135]
	v_mfma_f32_16x16x32_bf16 v[72:75], v[144:147], v[8:11], v[140:143]
	ds_read_b128 v[206:209], v92 offset:17536
	ds_read_b128 v[210:213], v92 offset:21888
	ds_read_b128 v[218:221], v92 offset:26240
	ds_read_b128 v[222:225], v92 offset:30592
	ds_read_b128 v[226:229], v92 offset:34944
	v_mfma_f32_16x16x32_bf16 v[76:79], v[152:155], v[8:11], v[148:151]
	s_waitcnt lgkmcnt(9)
	v_mfma_f32_16x16x32_bf16 v[0:3], v[160:163], v[8:11], v[0:3]
	s_nop 0
	ds_read_b128 v[88:91], v92 offset:192
	s_waitcnt lgkmcnt(9)
	v_mfma_f32_16x16x32_bf16 v[8:11], v[190:193], v[4:7], v[12:15]
	s_nop 2
	s_nop 0
	ds_read_b128 v[100:103], v92 offset:4544
	s_waitcnt lgkmcnt(9)
	v_mfma_f32_16x16x32_bf16 v[12:15], v[194:197], v[4:7], v[16:19]
	s_nop 2
	s_nop 0
	ds_read_b128 v[104:107], v92 offset:8896
	s_waitcnt lgkmcnt(9)
	v_mfma_f32_16x16x32_bf16 v[16:19], v[198:201], v[4:7], v[20:23]
	s_nop 2
	s_nop 0
	ds_read_b128 v[108:111], v92 offset:13248
	s_waitcnt lgkmcnt(9)
	v_mfma_f32_16x16x32_bf16 v[20:23], v[202:205], v[4:7], v[24:27]
	s_nop 2
	s_nop 0
	ds_read_b128 v[112:115], v92 offset:17600
	s_waitcnt lgkmcnt(9)
	ds_read_b128 v[186:189], v92 offset:39296
	ds_read_b128 v[190:193], v92 offset:43648
	ds_read_b128 v[194:197], v92 offset:48000
	ds_read_b128 v[198:201], v92 offset:52352
	ds_read_b128 v[202:205], v92 offset:56704
	v_mfma_f32_16x16x32_bf16 v[24:27], v[206:209], v[4:7], v[28:31]
	s_nop 2
	s_nop 0
	ds_read_b128 v[116:119], v92 offset:21952
	s_waitcnt lgkmcnt(14)
	v_mfma_f32_16x16x32_bf16 v[28:31], v[210:213], v[4:7], v[40:43]
	s_nop 2
	s_nop 0
	ds_read_b128 v[120:123], v92 offset:26304
	s_waitcnt lgkmcnt(14)
	v_mfma_f32_16x16x32_bf16 v[40:43], v[218:221], v[4:7], v[44:47]
	s_nop 2
	s_nop 0
	ds_read_b128 v[124:127], v92 offset:30656
	s_waitcnt lgkmcnt(14)
	v_mfma_f32_16x16x32_bf16 v[44:47], v[222:225], v[4:7], v[48:51]
	s_nop 2
	s_nop 0
	ds_read_b128 v[128:131], v92 offset:35008
	s_waitcnt lgkmcnt(14)
	v_mfma_f32_16x16x32_bf16 v[48:51], v[226:229], v[4:7], v[52:55]
	s_nop 2
	s_nop 0
	ds_read_b128 v[132:135], v92 offset:39360
	s_waitcnt lgkmcnt(9)
	ds_read_b128 v[206:209], v92 offset:61056
	ds_read_b128 v[210:213], v92 offset:65408
	v_mfma_f32_16x16x32_bf16 v[52:55], v[186:189], v[4:7], v[56:59]
	s_nop 2
	s_nop 0
	ds_read_b128 v[136:139], v92 offset:43712
	s_waitcnt lgkmcnt(11)
	v_mfma_f32_16x16x32_bf16 v[56:59], v[190:193], v[4:7], v[60:63]
	s_nop 2
	s_nop 0
	ds_read_b128 v[140:143], v92 offset:48064
	s_waitcnt lgkmcnt(11)
	v_mfma_f32_16x16x32_bf16 v[60:63], v[194:197], v[4:7], v[64:67]
	s_nop 2
	s_nop 0
	ds_read_b128 v[144:147], v92 offset:52416
	s_waitcnt lgkmcnt(11)
	v_mfma_f32_16x16x32_bf16 v[64:67], v[198:201], v[4:7], v[68:71]
	s_nop 2
	s_nop 0
	ds_read_b128 v[148:151], v92 offset:56768
	s_waitcnt lgkmcnt(11)
	v_mfma_f32_16x16x32_bf16 v[68:71], v[202:205], v[4:7], v[72:75]
	s_nop 2
	s_nop 0
	ds_read_b128 v[152:155], v92 offset:61120
	s_waitcnt lgkmcnt(6)
	v_mfma_f32_16x16x32_bf16 v[72:75], v[206:209], v[4:7], v[76:79]
	s_nop 2
	s_nop 0
	ds_read_b128 v[156:159], v92 offset:65472
	s_waitcnt lgkmcnt(6)
	v_mfma_f32_16x16x32_bf16 v[0:3], v[210:213], v[4:7], v[0:3]
	v_mfma_f32_16x16x32_bf16 v[76:79], v[88:91], v[32:35], v[8:11]
	v_mfma_f32_16x16x32_bf16 v[88:91], v[100:103], v[32:35], v[12:15]
	v_mfma_f32_16x16x32_bf16 v[100:103], v[104:107], v[32:35], v[16:19]
	v_mfma_f32_16x16x32_bf16 v[104:107], v[108:111], v[32:35], v[20:23]
	v_mfma_f32_16x16x32_bf16 v[108:111], v[112:115], v[32:35], v[24:27]
	v_mfma_f32_16x16x32_bf16 v[112:115], v[116:119], v[32:35], v[28:31]
	v_mfma_f32_16x16x32_bf16 v[40:43], v[120:123], v[32:35], v[40:43]
	v_mfma_f32_16x16x32_bf16 v[44:47], v[124:127], v[32:35], v[44:47]
	v_mfma_f32_16x16x32_bf16 v[28:31], v[128:131], v[32:35], v[48:51]
	v_mfma_f32_16x16x32_bf16 v[24:27], v[132:135], v[32:35], v[52:55]
	v_mfma_f32_16x16x32_bf16 v[20:23], v[136:139], v[32:35], v[56:59]
	v_mfma_f32_16x16x32_bf16 v[16:19], v[140:143], v[32:35], v[60:63]
	v_mfma_f32_16x16x32_bf16 v[12:15], v[144:147], v[32:35], v[64:67]
	v_mfma_f32_16x16x32_bf16 v[8:11], v[148:151], v[32:35], v[68:71]
	v_mfma_f32_16x16x32_bf16 v[4:7], v[152:155], v[32:35], v[72:75]
	s_waitcnt lgkmcnt(0)
; template <bool SAMPLE>
; __device__ __forceinline__ void mem_unit(const Params& p, int l, LAS unsigned char* lds, int unit, int tid, int wave, int lane) {
;     ...
;                 for (int e = 0; e < 4; ++e) mx = fmaxf(mx, a[e]);
;                 S[cc][tt] = a; }
;         mx = fmaxf(mx, __shfl_xor(mx, 16)); mx = fmaxf(mx, __shfl_xor(mx, 32));
;         float den = 0.f;
; #pragma unroll
;         for (int cc = 0; cc < 8; ++cc)
; #pragma unroll
;             for (int tt = 0; tt < 2; ++tt)
; #pragma unroll
;                 for (int e = 0; e < 4; ++e) { const float pe = __expf(S[cc][tt][e] - mx); S[cc][tt][e] = pe; den += pe; }
	v_mfma_f32_16x16x32_bf16 v[0:3], v[156:159], v[32:35], v[0:3]
	v_max3_f32 v32, v76, s24, v77
	v_max3_f32 v32, v32, v78, v79
	v_max3_f32 v32, v32, v88, v89
	v_max3_f32 v32, v32, v90, v91
	v_max3_f32 v32, v32, v100, v101
	v_max3_f32 v32, v32, v102, v103
	v_max3_f32 v32, v32, v104, v105
	v_max3_f32 v32, v32, v106, v107
	v_max3_f32 v32, v32, v108, v109
	v_max3_f32 v32, v32, v110, v111
	v_max3_f32 v32, v32, v112, v113
	v_max3_f32 v32, v32, v114, v115
	v_max3_f32 v32, v32, v40, v41
	v_max3_f32 v32, v32, v42, v43
	v_max3_f32 v32, v32, v44, v45
	v_max3_f32 v32, v32, v46, v47
	v_max3_f32 v32, v32, v28, v29
	v_max3_f32 v32, v32, v30, v31
	v_max3_f32 v32, v32, v24, v25
	v_max3_f32 v32, v32, v26, v27
	v_max3_f32 v32, v32, v20, v21
	v_max3_f32 v32, v32, v22, v23
	v_max3_f32 v32, v32, v16, v17
	v_max3_f32 v32, v32, v18, v19
	v_max3_f32 v32, v32, v12, v13
	v_max3_f32 v32, v32, v14, v15
	v_max3_f32 v32, v32, v8, v9
	v_max3_f32 v32, v32, v10, v11
	v_max3_f32 v32, v32, v4, v5
	v_max3_f32 v32, v32, v6, v7
	v_max3_f32 v32, v32, v0, v1
	v_max3_f32 v32, v32, v2, v3
	ds_bpermute_b32 v33, v38, v32
	s_waitcnt lgkmcnt(0)
	v_max_f32_e32 v33, v33, v33
	v_max_f32_e32 v32, v32, v33
	ds_bpermute_b32 v33, v39, v32
	s_waitcnt lgkmcnt(0)
	v_max_f32_e32 v33, v33, v33
	v_max_f32_e32 v32, v32, v33
	v_sub_f32_e32 v33, v76, v32
	v_sub_f32_e32 v34, v77, v32
	v_mul_f32_e32 v33, 0x3fb8aa3b, v33
	v_sub_f32_e32 v35, v78, v32
	v_mul_f32_e32 v34, 0x3fb8aa3b, v34
	v_exp_f32_e32 v33, v33
	v_sub_f32_e32 v48, v79, v32
	v_mul_f32_e32 v35, 0x3fb8aa3b, v35
	v_exp_f32_e32 v34, v34
	v_sub_f32_e32 v49, v88, v32
	v_mul_f32_e32 v48, 0x3fb8aa3b, v48
	v_exp_f32_e32 v35, v35
	v_sub_f32_e32 v50, v89, v32
	v_mul_f32_e32 v49, 0x3fb8aa3b, v49
	v_exp_f32_e32 v48, v48
	v_sub_f32_e32 v51, v90, v32
	v_mul_f32_e32 v50, 0x3fb8aa3b, v50
	v_exp_f32_e32 v49, v49
	v_add_f32_e32 v69, 0, v33
	v_sub_f32_e32 v52, v91, v32
	v_mul_f32_e32 v51, 0x3fb8aa3b, v51
	v_exp_f32_e32 v50, v50
	v_add_f32_e32 v69, v34, v69
	v_sub_f32_e32 v53, v100, v32
	v_mul_f32_e32 v52, 0x3fb8aa3b, v52
	v_exp_f32_e32 v51, v51
	v_add_f32_e32 v69, v35, v69
	v_sub_f32_e32 v54, v101, v32
	v_mul_f32_e32 v53, 0x3fb8aa3b, v53
	v_exp_f32_e32 v52, v52
	v_add_f32_e32 v69, v48, v69
	v_sub_f32_e32 v55, v102, v32
	v_mul_f32_e32 v54, 0x3fb8aa3b, v54
	v_exp_f32_e32 v53, v53
	v_add_f32_e32 v69, v49, v69
	v_sub_f32_e32 v56, v103, v32
	v_mul_f32_e32 v55, 0x3fb8aa3b, v55
	v_exp_f32_e32 v54, v54
	v_add_f32_e32 v69, v50, v69
	v_sub_f32_e32 v57, v104, v32
	v_mul_f32_e32 v56, 0x3fb8aa3b, v56
	v_exp_f32_e32 v55, v55
	v_add_f32_e32 v69, v51, v69
	v_sub_f32_e32 v58, v105, v32
	v_mul_f32_e32 v57, 0x3fb8aa3b, v57
	v_exp_f32_e32 v56, v56
	v_add_f32_e32 v69, v52, v69
	v_sub_f32_e32 v59, v106, v32
	v_mul_f32_e32 v58, 0x3fb8aa3b, v58
	v_exp_f32_e32 v57, v57
	v_add_f32_e32 v69, v53, v69
	v_sub_f32_e32 v60, v107, v32
	v_mul_f32_e32 v59, 0x3fb8aa3b, v59
	v_exp_f32_e32 v58, v58
	v_add_f32_e32 v69, v54, v69
	v_sub_f32_e32 v61, v108, v32
	v_mul_f32_e32 v60, 0x3fb8aa3b, v60
	v_exp_f32_e32 v59, v59
	v_add_f32_e32 v69, v55, v69
	v_sub_f32_e32 v62, v109, v32
	v_mul_f32_e32 v61, 0x3fb8aa3b, v61
	v_exp_f32_e32 v60, v60
	v_add_f32_e32 v69, v56, v69
	v_sub_f32_e32 v63, v110, v32
	v_mul_f32_e32 v62, 0x3fb8aa3b, v62
	v_exp_f32_e32 v61, v61
	v_add_f32_e32 v69, v57, v69
	v_sub_f32_e32 v64, v111, v32
	v_mul_f32_e32 v63, 0x3fb8aa3b, v63
	v_exp_f32_e32 v62, v62
	v_add_f32_e32 v69, v58, v69
	v_sub_f32_e32 v65, v112, v32
	v_mul_f32_e32 v64, 0x3fb8aa3b, v64
	v_exp_f32_e32 v63, v63
	v_add_f32_e32 v69, v59, v69
	v_sub_f32_e32 v66, v113, v32
	v_mul_f32_e32 v65, 0x3fb8aa3b, v65
	v_exp_f32_e32 v64, v64
	v_add_f32_e32 v69, v60, v69
	v_sub_f32_e32 v67, v114, v32
	v_mul_f32_e32 v66, 0x3fb8aa3b, v66
	v_exp_f32_e32 v65, v65
	v_add_f32_e32 v69, v61, v69
	v_sub_f32_e32 v68, v115, v32
	v_mul_f32_e32 v67, 0x3fb8aa3b, v67
	v_exp_f32_e32 v66, v66
	v_add_f32_e32 v69, v62, v69
	v_sub_f32_e32 v40, v40, v32
	v_mul_f32_e32 v68, 0x3fb8aa3b, v68
	v_exp_f32_e32 v67, v67
	v_add_f32_e32 v69, v63, v69
	v_sub_f32_e32 v41, v41, v32
	v_mul_f32_e32 v40, 0x3fb8aa3b, v40
	v_exp_f32_e32 v68, v68
	v_add_f32_e32 v69, v64, v69
	v_sub_f32_e32 v42, v42, v32
	v_mul_f32_e32 v41, 0x3fb8aa3b, v41
	v_exp_f32_e32 v40, v40
	v_add_f32_e32 v69, v65, v69
	v_sub_f32_e32 v43, v43, v32
	v_mul_f32_e32 v42, 0x3fb8aa3b, v42
	v_exp_f32_e32 v41, v41
	v_add_f32_e32 v69, v66, v69
	v_sub_f32_e32 v44, v44, v32
	v_mul_f32_e32 v43, 0x3fb8aa3b, v43
	v_exp_f32_e32 v42, v42
	v_add_f32_e32 v69, v67, v69
	v_sub_f32_e32 v45, v45, v32
	v_mul_f32_e32 v44, 0x3fb8aa3b, v44
	v_exp_f32_e32 v43, v43
	v_add_f32_e32 v69, v68, v69
	v_sub_f32_e32 v46, v46, v32
	v_mul_f32_e32 v45, 0x3fb8aa3b, v45
	v_exp_f32_e32 v44, v44
	v_add_f32_e32 v69, v40, v69
	v_sub_f32_e32 v47, v47, v32
	v_mul_f32_e32 v46, 0x3fb8aa3b, v46
	v_exp_f32_e32 v45, v45
	v_add_f32_e32 v69, v41, v69
	v_sub_f32_e32 v28, v28, v32
	v_mul_f32_e32 v47, 0x3fb8aa3b, v47
	v_exp_f32_e32 v46, v46
	v_add_f32_e32 v69, v42, v69
	v_sub_f32_e32 v29, v29, v32
	v_mul_f32_e32 v28, 0x3fb8aa3b, v28
	v_exp_f32_e32 v47, v47
	v_add_f32_e32 v69, v43, v69
	v_exp_f32_e32 v28, v28
	v_add_f32_e32 v69, v44, v69
	v_mul_f32_e32 v29, 0x3fb8aa3b, v29
	v_sub_f32_e32 v30, v30, v32
	v_sub_f32_e32 v24, v24, v32
	v_add_f32_e32 v69, v45, v69
	v_exp_f32_e32 v29, v29
	v_mul_f32_e32 v30, 0x3fb8aa3b, v30
	v_sub_f32_e32 v31, v31, v32
	v_mul_f32_e32 v24, 0x3fb8aa3b, v24
	v_add_f32_e32 v69, v46, v69
	v_exp_f32_e32 v30, v30
	v_mul_f32_e32 v31, 0x3fb8aa3b, v31
	v_exp_f32_e32 v70, v24
	v_sub_f32_e32 v24, v25, v32
	v_add_f32_e32 v69, v47, v69
	v_exp_f32_e32 v31, v31
	v_mul_f32_e32 v24, 0x3fb8aa3b, v24
	v_add_f32_e32 v69, v28, v69
	v_exp_f32_e32 v71, v24
; #define LAS __attribute__((address_space(3)))
; __device__ __forceinline__ unsigned pk2(float lo, float hi) { return pg8::cvt_pk_bf16(lo, hi); }
; __device__ __forceinline__ bf16x8 pack8(const float (&o)[8]) { v4u w; w.x = pk2(o[0], o[1]); w.y = pk2(o[2], o[3]); w.z = pk2(o[4], o[5]); w.w = pk2(o[6], o[7]); return __builtin_bit_cast(bf16x8, w); }
; __device__ __forceinline__ v2u vtr(const LAS bf16* p) { return __builtin_bit_cast(v2u, __builtin_amdgcn_ds_read_tr16_b64_v4i16((LAS v4i16_t*)p)); }
; template <bool SAMPLE>
; __device__ __forceinline__ void mem_unit(const Params& p, int l, LAS unsigned char* lds, int unit, int tid, int wave, int lane) {
;     ...
;                 for (int e = 0; e < 4; ++e) { const float pe = __expf(S[cc][tt][e] - mx); S[cc][tt][e] = pe; den += pe; }
;         den += __shfl_xor(den, 16); den += __shfl_xor(den, 32);
;         const float rden = 1.f / den;
;         bf16x8 pf[8];
; #pragma unroll
;         for (int cc = 0; cc < 8; ++cc) { float t8[8];
; #pragma unroll
;             for (int e = 0; e < 4; ++e) { t8[e] = S[cc][0][e]; t8[4 + e] = S[cc][1][e]; }
;             pf[cc] = pack8(t8); }
; #pragma unroll
;         for (int dt = 0; dt < 8; ++dt) { f32x4 o = (f32x4){0.f, 0.f, 0.f, 0.f};
; #pragma unroll
;             for (int cc = 0; cc < 8; ++cc) { const LAS bf16* vp = Vt + (32 * cc + 4 * kq + (q16 >> 2)) * MEM_VS + 16 * dt + 4 * (q16 & 3);
;                 const v2u lo = vtr(vp), hi = vtr(vp + 16 * MEM_VS);
;                 v4u av; av.x = lo.x; av.y = lo.y; av.z = hi.x; av.w = hi.y;
;                 o = __builtin_amdgcn_mfma_f32_16x16x32_bf16(__builtin_bit_cast(bf16x8, av), pf[cc], o, 0, 0, 0); }
;             if (st) { v2u w; w.x = pk2(o[0] * rden, o[1] * rden); w.y = pk2(o[2] * rden, o[3] * rden);
;                 *(v2u*)(MO + row * 512 + h * 128 + 16 * dt + 4 * kq) = w; } }
	v_sub_f32_e32 v24, v26, v32
	v_add_f32_e32 v69, v29, v69
	v_mul_f32_e32 v24, 0x3fb8aa3b, v24
	v_add_f32_e32 v69, v30, v69
	v_exp_f32_e32 v72, v24
	v_sub_f32_e32 v24, v27, v32
	v_sub_f32_e32 v20, v20, v32
	v_add_f32_e32 v69, v31, v69
	v_mul_f32_e32 v24, 0x3fb8aa3b, v24
	v_mul_f32_e32 v20, 0x3fb8aa3b, v20
	v_exp_f32_e32 v73, v24
	v_add_f32_e32 v24, v70, v69
	v_exp_f32_e32 v69, v20
	v_sub_f32_e32 v20, v21, v32
	v_mul_f32_e32 v20, 0x3fb8aa3b, v20
	v_exp_f32_e32 v74, v20
	v_sub_f32_e32 v20, v22, v32
	v_sub_f32_e32 v16, v16, v32
	v_mul_f32_e32 v20, 0x3fb8aa3b, v20
	v_mul_f32_e32 v16, 0x3fb8aa3b, v16
	v_add_f32_e32 v24, v71, v24
	v_exp_f32_e32 v75, v20
	v_sub_f32_e32 v20, v23, v32
	v_exp_f32_e32 v77, v16
	v_sub_f32_e32 v16, v17, v32
	v_add_f32_e32 v24, v72, v24
	v_mul_f32_e32 v20, 0x3fb8aa3b, v20
	v_mul_f32_e32 v16, 0x3fb8aa3b, v16
	v_add_f32_e32 v24, v73, v24
	v_exp_f32_e32 v76, v20
	v_exp_f32_e32 v78, v16
	v_sub_f32_e32 v16, v18, v32
	v_sub_f32_e32 v12, v12, v32
	v_add_f32_e32 v20, v69, v24
	v_mul_f32_e32 v16, 0x3fb8aa3b, v16
	v_mul_f32_e32 v12, 0x3fb8aa3b, v12
	v_add_f32_e32 v20, v74, v20
	v_exp_f32_e32 v79, v16
	v_sub_f32_e32 v16, v19, v32
	v_exp_f32_e32 v89, v12
	v_sub_f32_e32 v12, v13, v32
	v_add_f32_e32 v20, v75, v20
	v_mul_f32_e32 v16, 0x3fb8aa3b, v16
	v_mul_f32_e32 v12, 0x3fb8aa3b, v12
	v_add_f32_e32 v20, v76, v20
	v_exp_f32_e32 v88, v16
	v_exp_f32_e32 v90, v12
	v_sub_f32_e32 v12, v14, v32
	v_sub_f32_e32 v8, v8, v32
	v_add_f32_e32 v16, v77, v20
	v_mul_f32_e32 v12, 0x3fb8aa3b, v12
	v_mul_f32_e32 v8, 0x3fb8aa3b, v8
	v_add_f32_e32 v16, v78, v16
	v_exp_f32_e32 v91, v12
	v_sub_f32_e32 v12, v15, v32
	v_exp_f32_e32 v93, v8
	v_sub_f32_e32 v8, v9, v32
	v_add_f32_e32 v16, v79, v16
	v_mul_f32_e32 v12, 0x3fb8aa3b, v12
	v_mul_f32_e32 v8, 0x3fb8aa3b, v8
	v_add_f32_e32 v16, v88, v16
	v_exp_f32_e32 v92, v12
	v_exp_f32_e32 v100, v8
	v_sub_f32_e32 v8, v10, v32
	v_sub_f32_e32 v4, v4, v32
	v_add_f32_e32 v12, v89, v16
	v_mul_f32_e32 v8, 0x3fb8aa3b, v8
	v_mul_f32_e32 v4, 0x3fb8aa3b, v4
	v_add_f32_e32 v12, v90, v12
	v_exp_f32_e32 v101, v8
	v_sub_f32_e32 v8, v11, v32
	v_exp_f32_e32 v103, v4
	v_sub_f32_e32 v4, v5, v32
	v_add_f32_e32 v12, v91, v12
	v_mul_f32_e32 v8, 0x3fb8aa3b, v8
	v_mul_f32_e32 v4, 0x3fb8aa3b, v4
	v_add_f32_e32 v12, v92, v12
	v_exp_f32_e32 v102, v8
	v_exp_f32_e32 v104, v4
	v_sub_f32_e32 v4, v6, v32
	v_sub_f32_e32 v0, v0, v32
	v_add_f32_e32 v8, v93, v12
	v_mul_f32_e32 v4, 0x3fb8aa3b, v4
	v_mul_f32_e32 v0, 0x3fb8aa3b, v0
	v_add_f32_e32 v8, v100, v8
	v_exp_f32_e32 v105, v4
	v_sub_f32_e32 v4, v7, v32
	v_exp_f32_e32 v107, v0
	v_sub_f32_e32 v0, v1, v32
	v_add_f32_e32 v8, v101, v8
	v_mul_f32_e32 v4, 0x3fb8aa3b, v4
	v_mul_f32_e32 v0, 0x3fb8aa3b, v0
	v_add_f32_e32 v8, v102, v8
	v_exp_f32_e32 v106, v4
	v_exp_f32_e32 v108, v0
	v_sub_f32_e32 v0, v2, v32
	v_add_f32_e32 v4, v103, v8
	v_mul_f32_e32 v0, 0x3fb8aa3b, v0
	v_add_f32_e32 v4, v104, v4
	v_exp_f32_e32 v109, v0
	v_sub_f32_e32 v0, v3, v32
	v_add_f32_e32 v4, v105, v4
	v_mul_f32_e32 v0, 0x3fb8aa3b, v0
	v_add_f32_e32 v4, v106, v4
	v_exp_f32_e32 v32, v0
	v_add_f32_e32 v0, v107, v4
	v_add_f32_e32 v0, v108, v0
	v_add_f32_e32 v0, v109, v0
	v_add_f32_e32 v0, v32, v0
	ds_bpermute_b32 v1, v38, v0
	v_cvt_pk_bf16_f32 v24, v33, v34
	v_cvt_pk_bf16_f32 v25, v35, v48
	v_cvt_pk_bf16_f32 v26, v49, v50
	v_cvt_pk_bf16_f32 v27, v51, v52
	s_waitcnt lgkmcnt(0)
	v_add_f32_e32 v0, v0, v1
	ds_bpermute_b32 v1, v39, v0
	v_cvt_pk_bf16_f32 v20, v53, v54
	v_cvt_pk_bf16_f32 v21, v55, v56
	v_cvt_pk_bf16_f32 v22, v57, v58
	v_cvt_pk_bf16_f32 v23, v59, v60
	s_waitcnt lgkmcnt(0)
	v_add_f32_e32 v39, v0, v1
	v_cvt_pk_bf16_f32 v16, v61, v62
	v_cvt_pk_bf16_f32 v17, v63, v64
	v_cvt_pk_bf16_f32 v18, v65, v66
	v_cvt_pk_bf16_f32 v19, v67, v68
	v_cvt_pk_bf16_f32 v12, v40, v41
	v_cvt_pk_bf16_f32 v13, v42, v43
	v_cvt_pk_bf16_f32 v14, v44, v45
	v_cvt_pk_bf16_f32 v15, v46, v47
	v_cvt_pk_bf16_f32 v8, v28, v29
	v_cvt_pk_bf16_f32 v9, v30, v31
	v_cvt_pk_bf16_f32 v10, v70, v71
	v_cvt_pk_bf16_f32 v11, v72, v73
	v_cvt_pk_bf16_f32 v4, v69, v74
	v_cvt_pk_bf16_f32 v5, v75, v76
	v_cvt_pk_bf16_f32 v6, v77, v78
	v_cvt_pk_bf16_f32 v7, v79, v88
	v_cvt_pk_bf16_f32 v0, v89, v90
	v_cvt_pk_bf16_f32 v1, v91, v92
	v_cvt_pk_bf16_f32 v2, v93, v100
	v_cvt_pk_bf16_f32 v3, v101, v102
	v_cvt_pk_bf16_f32 v28, v103, v104
	v_cvt_pk_bf16_f32 v29, v105, v106
	v_cvt_pk_bf16_f32 v30, v107, v108
	v_cvt_pk_bf16_f32 v31, v109, v32
	v_lshlrev_b32_e32 v52, 2, v37
	v_lshrrev_b32_e32 v32, 2, v36
	v_add_u32_e32 v32, v32, v52
	v_lshlrev_b32_e32 v33, 3, v36
	v_and_b32_e32 v33, 24, v33
	v_mul_lo_u32 v32, v32, s22
	v_add3_u32 v38, s90, v33, v32
	ds_read_b64_tr_b16 v[194:195], v38
	ds_read_b64_tr_b16 v[196:197], v38 offset:4352
	ds_read_b64_tr_b16 v[198:199], v38 offset:8704
	ds_read_b64_tr_b16 v[200:201], v38 offset:13056
	ds_read_b64_tr_b16 v[202:203], v38 offset:17408
	ds_read_b64_tr_b16 v[204:205], v38 offset:21760
	ds_read_b64_tr_b16 v[206:207], v38 offset:26112
	ds_read_b64_tr_b16 v[208:209], v38 offset:30464
	ds_read_b64_tr_b16 v[210:211], v38 offset:34816
	ds_read_b64_tr_b16 v[212:213], v38 offset:39168
	s_nop 3
	s_waitcnt lgkmcnt(8)
	v_mfma_f32_16x16x32_bf16 v[32:35], v[194:197], v[24:27], 0
	s_nop 3
	v_div_scale_f32 v53, s[2:3], v39, v39, 1.0
	s_waitcnt lgkmcnt(6)
	v_mfma_f32_16x16x32_bf16 v[32:35], v[198:201], v[20:23], v[32:35]
	s_nop 1
	v_rcp_f32_e32 v37, v53
	s_add_u32 s2, s70, s0
	s_waitcnt lgkmcnt(4)
	v_mfma_f32_16x16x32_bf16 v[32:35], v[202:205], v[16:19], v[32:35]
	ds_read_b64_tr_b16 v[44:45], v38 offset:43520
	ds_read_b64_tr_b16 v[46:47], v38 offset:47872
	v_cmp_gt_i32_e64 s[0:1], 8, v36
	v_fma_f32 v36, -v53, v37, 1.0
	s_waitcnt lgkmcnt(4)
	v_mfma_f32_16x16x32_bf16 v[32:35], v[206:209], v[12:15], v[32:35]
	ds_read_b64_tr_b16 v[48:49], v38 offset:52224
	ds_read_b64_tr_b16 v[50:51], v38 offset:56576
	v_fmac_f32_e32 v37, v36, v37
	v_div_scale_f32 v36, vcc, 1.0, v39, 1.0
	s_waitcnt lgkmcnt(4)
	v_mfma_f32_16x16x32_bf16 v[32:35], v[210:213], v[8:11], v[32:35]
	ds_read_b64_tr_b16 v[40:41], v38 offset:60928
	ds_read_b64_tr_b16 v[42:43], v38 offset:65280
	v_mul_f32_e32 v54, v36, v37
	v_fma_f32 v55, -v53, v54, v36
	s_waitcnt lgkmcnt(4)
	v_mfma_f32_16x16x32_bf16 v[32:35], v[44:47], v[4:7], v[32:35]
	v_fmac_f32_e32 v54, v55, v37
	v_fma_f32 v36, -v53, v54, v36
	s_addc_u32 s3, s71, 0
	s_waitcnt lgkmcnt(2)
	v_mfma_f32_16x16x32_bf16 v[32:35], v[48:51], v[0:3], v[32:35]
	v_div_fmas_f32 v36, v36, v37, v54
	v_div_fixup_f32 v39, v36, v39, 1.0
	v_lshl_add_u64 v[36:37], s[2:3], 0, v[82:83]
	s_waitcnt lgkmcnt(0)
	v_mfma_f32_16x16x32_bf16 v[32:35], v[40:43], v[28:31], v[32:35]
	v_ashrrev_i32_e32 v53, 31, v52
	v_lshl_add_u64 v[36:37], v[52:53], 1, v[36:37]
	s_and_saveexec_b64 s[2:3], s[0:1]
	s_cbranch_execz .LBB0_2734
	s_nop 3
	v_mul_f32_e32 v32, v32, v39
	v_mul_f32_e32 v33, v33, v39
	v_cvt_pk_bf16_f32 v32, v32, v33
	v_mul_f32_e32 v33, v34, v39
	v_mul_f32_e32 v34, v35, v39
	v_cvt_pk_bf16_f32 v33, v33, v34
	global_store_dwordx2 v[36:37], v[32:33], off
